# attention loops without per-step s_setprio flips; in-proj epilogue preloads row stats and gate biases; combine-phase loads hoisted
# speedup vs baseline: 1.0051x; 1.0051x over previous
; __global__ void __launch_bounds__(NTHREADS, 2) mk_fwd(Args args) {
;     ...
;                 for (int m = gw; m < MH; m += NGW) {
;                     const u32x4 w1 = *(const u32x4*)(OD + (size_t)m * DM + (2 * hh) * 128 + d8), w2 = *(const u32x4*)(OD + (size_t)m * DM + (2 * hh + 1) * 128 + d8);
;                     f32x4 ya, yb;
;                     ya[0] = bf_lo(w1.x) - lam * bf_lo(w2.x); ya[1] = bf_hi(w1.x) - lam * bf_hi(w2.x); ya[2] = bf_lo(w1.y) - lam * bf_lo(w2.y); ya[3] = bf_hi(w1.y) - lam * bf_hi(w2.y);
;                     yb[0] = bf_lo(w1.z) - lam * bf_lo(w2.z); yb[1] = bf_hi(w1.z) - lam * bf_hi(w2.z); yb[2] = bf_lo(w1.w) - lam * bf_lo(w2.w); yb[3] = bf_hi(w1.w) - lam * bf_hi(w2.w);
;                     float ss = (ya[0] * ya[0] + ya[1] * ya[1]) + (ya[2] * ya[2] + ya[3] * ya[3]) + (yb[0] * yb[0] + yb[1] * yb[1]) + (yb[2] * yb[2] + yb[3] * yb[3]);
;                     ss += __shfl_xor(ss, 1); ss += __shfl_xor(ss, 2); ss += __shfl_xor(ss, 4); ss += __shfl_xor(ss, 8);
;                     const float rstd = rsqrtf(ss * (1.f / 128.f) + EPS);
;                     ya = ya * rstd * gv0; yb = yb * rstd * gv1;
;                     u32x4 ow; ow.x = pk2(ya[0], ya[1]); ow.y = pk2(ya[2], ya[3]); ow.z = pk2(yb[0], yb[1]); ow.w = pk2(yb[2], yb[3]);
;                     const float l0 = LSE[(size_t)m * 4 + hh], l1 = LSE[(size_t)MH * 4 + (size_t)m * 4 + hh], l2 = LSE[(size_t)2 * MH * 4 + (size_t)m * 4 + hh];
;                     const float lm = fmaxf(l0, fmaxf(l1, l2)); const float e0 = __expf(l0 - lm), e1 = __expf(l1 - lm), e2 = __expf(l2 - lm); const float ri = 1.f / (e0 + e1 + e2);
;                     bf16_t* pr = P + (size_t)m * NIN + PC_DIL + hh * 64 + d4;
;                     const u32x2 wv0 = *(const u32x2*)(pr), wv1 = *(const u32x2*)(pr + 768), wv2 = *(const u32x2*)(pr + 1536);
;                     const float a0 = e0 * ri, a1 = e1 * ri, a2 = e2 * ri;
;                     const float ob0 = a0 * bf_lo(wv0.x) + a1 * bf_lo(wv1.x) + a2 * bf_lo(wv2.x), ob1 = a0 * bf_hi(wv0.x) + a1 * bf_hi(wv1.x) + a2 * bf_hi(wv2.x);
;                     const float ob2 = a0 * bf_lo(wv0.y) + a1 * bf_lo(wv1.y) + a2 * bf_lo(wv2.y), ob3 = a0 * bf_hi(wv0.y) + a1 * bf_hi(wv1.y) + a2 * bf_hi(wv2.y);
;                     *(u32x4*)(P + (size_t)m * NIN + PC_DQ + hh * 128 + d8) = ow;
;                     u32x2 o2; o2.x = pk2(ob0, ob1); o2.y = pk2(ob2, ob3); *(u32x2*)pr = o2;
.LBB0_200:
	v_lshl_add_u64 v[2:3], s[80:81], 0, v[18:19]
	v_add_co_u32_e32 v28, vcc, 0x30400000, v2
	s_nop 0
	s_nop 0
	v_addc_co_u32_e32 v29, vcc, 0, v3, vcc
	global_load_dwordx4 v[2:5], v[28:29], off
	s_nop 0
	global_load_dwordx4 v[28:31], v[28:29], off offset:256
	v_lshl_add_u64 v[54:55], s[80:81], 0, v[16:17]
	v_add_co_u32_e32 v56, vcc, 0x38400000, v54
	s_nop 1
	v_addc_co_u32_e32 v57, vcc, 0, v55, vcc
	global_load_dword v44, v[56:57], off
	v_add_co_u32_e32 v56, vcc, 0x38480000, v54
	s_nop 1
	v_addc_co_u32_e32 v57, vcc, 0, v55, vcc
	global_load_dword v45, v[56:57], off
	v_add_co_u32_e32 v56, vcc, 0x38500000, v54
	s_nop 1
	v_addc_co_u32_e32 v57, vcc, 0, v55, vcc
	global_load_dword v46, v[56:57], off
	v_lshl_add_u64 v[60:61], s[80:81], 0, v[20:21]
	global_load_dwordx2 v[48:49], v[60:61], off offset:-1536
	global_load_dwordx2 v[50:51], v[60:61], off
	global_load_dwordx2 v[52:53], v[60:61], off offset:1536
	v_lshl_add_u64 v[42:43], s[80:81], 0, v[22:23]
	s_add_i32 s12, s12, s76
	v_lshl_add_u64 v[18:19], v[18:19], 0, s[8:9]
	v_lshl_add_u64 v[22:23], v[22:23], 0, s[10:11]
	s_cmpk_gt_i32 s12, 0x7fff
	s_waitcnt vmcnt(7)
	v_lshlrev_b32_e32 v32, 16, v2
	v_and_b32_e32 v33, 0xffff0000, v2
	s_waitcnt vmcnt(6)
	v_lshlrev_b32_e32 v34, 16, v28
	v_and_b32_e32 v35, 0xffff0000, v28
	v_lshlrev_b32_e32 v2, 16, v3
	v_and_b32_e32 v3, 0xffff0000, v3
	v_lshlrev_b32_e32 v28, 16, v29
	v_and_b32_e32 v29, 0xffff0000, v29
	v_pk_fma_f32 v[32:33], v[14:15], v[34:35], v[32:33] neg_lo:[1,0,0] neg_hi:[1,0,0]
	v_pk_fma_f32 v[2:3], v[14:15], v[28:29], v[2:3] neg_lo:[1,0,0] neg_hi:[1,0,0]
	v_lshlrev_b32_e32 v28, 16, v4
	v_and_b32_e32 v29, 0xffff0000, v4
	v_lshlrev_b32_e32 v34, 16, v30
	v_and_b32_e32 v35, 0xffff0000, v30
	v_lshlrev_b32_e32 v4, 16, v5
	v_and_b32_e32 v5, 0xffff0000, v5
	v_lshlrev_b32_e32 v30, 16, v31
	v_and_b32_e32 v31, 0xffff0000, v31
	v_pk_fma_f32 v[28:29], v[14:15], v[34:35], v[28:29] neg_lo:[1,0,0] neg_hi:[1,0,0]
	v_pk_fma_f32 v[4:5], v[14:15], v[30:31], v[4:5] neg_lo:[1,0,0] neg_hi:[1,0,0]
	v_mov_b32_e32 v34, v33
	v_mov_b32_e32 v35, v3
	v_mov_b32_e32 v30, v32
	v_mov_b32_e32 v31, v2
	v_pk_mul_f32 v[34:35], v[34:35], v[34:35]
	v_mov_b32_e32 v36, v5
	v_mov_b32_e32 v37, v29
	v_pk_fma_f32 v[30:31], v[30:31], v[30:31], v[34:35]
	v_mov_b32_e32 v34, v4
	v_mov_b32_e32 v35, v28
	v_pk_mul_f32 v[36:37], v[36:37], v[36:37]
	v_add_f32_e32 v27, v30, v31
	v_pk_fma_f32 v[34:35], v[34:35], v[34:35], v[36:37]
	s_nop 0
	v_add_f32_e32 v27, v35, v27
	v_add_f32_e32 v27, v34, v27
	ds_bpermute_b32 v30, v0, v27
	s_waitcnt lgkmcnt(0)
	v_add_f32_e32 v27, v27, v30
	ds_bpermute_b32 v30, v24, v27
	s_waitcnt lgkmcnt(0)
	v_add_f32_e32 v27, v27, v30
	ds_bpermute_b32 v30, v25, v27
	s_waitcnt lgkmcnt(0)
	v_add_f32_e32 v27, v27, v30
	ds_bpermute_b32 v30, v26, v27
	s_waitcnt lgkmcnt(0)
	v_add_f32_e32 v27, v27, v30
	v_fmamk_f32 v27, v27, 0x3c000000, v235
	v_cmp_gt_f32_e32 vcc, s58, v27
	v_mul_f32_e32 v30, 0x4b800000, v27
	s_nop 0
	v_cndmask_b32_e32 v27, v27, v30, vcc
	v_rsq_f32_e32 v27, v27
	s_nop 0
	v_mul_f32_e32 v30, 0x45800000, v27
	v_cndmask_b32_e32 v30, v27, v30, vcc
	v_pk_mul_f32 v[32:33], v[32:33], v[30:31] op_sel_hi:[1,0]
	v_pk_mul_f32 v[2:3], v[2:3], v[30:31] op_sel_hi:[1,0]
	v_pk_mul_f32 v[28:29], v[28:29], v[30:31] op_sel_hi:[1,0]
	v_pk_mul_f32 v[34:35], v[6:7], v[2:3]
	v_pk_mul_f32 v[2:3], v[8:9], v[32:33]
	v_pk_mul_f32 v[4:5], v[4:5], v[30:31] op_sel_hi:[1,0]
	v_bfe_u32 v27, v2, 16, 1
	v_add3_u32 v2, v2, v27, s68
	v_bfe_u32 v27, v3, 16, 1
	v_lshrrev_b32_e32 v2, 16, v2
	v_add3_u32 v3, v3, v27, s68
	v_and_or_b32 v2, v3, s64, v2
	v_bfe_u32 v3, v34, 16, 1
	v_add3_u32 v3, v34, v3, s68
	v_bfe_u32 v27, v35, 16, 1
	v_pk_mul_f32 v[30:31], v[10:11], v[4:5]
	v_pk_mul_f32 v[4:5], v[12:13], v[28:29]
	v_lshrrev_b32_e32 v3, 16, v3
	v_add3_u32 v27, v35, v27, s68
	v_and_or_b32 v3, v27, s64, v3
	v_bfe_u32 v27, v4, 16, 1
	v_add3_u32 v4, v4, v27, s68
	v_bfe_u32 v27, v5, 16, 1
	v_lshrrev_b32_e32 v4, 16, v4
	v_add3_u32 v5, v5, v27, s68
	v_and_or_b32 v4, v5, s64, v4
	v_bfe_u32 v5, v30, 16, 1
	v_add3_u32 v5, v30, v5, s68
	v_bfe_u32 v27, v31, 16, 1
	v_lshrrev_b32_e32 v5, 16, v5
	v_add3_u32 v27, v31, v27, s68
	v_and_or_b32 v5, v27, s64, v5
	v_lshl_add_u64 v[16:17], v[16:17], 0, s[6:7]
	s_waitcnt vmcnt(3)
	v_max3_f32 v32, v44, v45, v46
	v_sub_f32_e32 v27, v44, v32
	v_mul_f32_e32 v27, 0x3fb8aa3b, v27
	v_exp_f32_e32 v29, v27
	v_sub_f32_e32 v27, v45, v32
	v_mul_f32_e32 v27, 0x3fb8aa3b, v27
	v_exp_f32_e32 v28, v27
	v_sub_f32_e32 v27, v46, v32
	v_mul_f32_e32 v27, 0x3fb8aa3b, v27
	v_exp_f32_e32 v27, v27
	v_add_f32_e32 v30, v29, v28
	v_add_f32_e32 v30, v27, v30
	v_div_scale_f32 v31, s[0:1], v30, v30, 1.0
	v_rcp_f32_e32 v32, v31
	s_nop 0
	v_fma_f32 v33, -v31, v32, 1.0
	v_fmac_f32_e32 v32, v33, v32
	v_div_scale_f32 v33, vcc, 1.0, v30, 1.0
	v_mul_f32_e32 v34, v33, v32
	v_fma_f32 v35, -v31, v34, v33
	v_fmac_f32_e32 v34, v35, v32
	v_fma_f32 v31, -v31, v34, v33
	v_div_fmas_f32 v31, v31, v32, v34
	v_div_fixup_f32 v30, v31, v30, 1.0
	global_store_dwordx4 v[42:43], v[2:5], off
	v_mul_f32_e32 v40, v27, v30
	v_lshl_add_u64 v[20:21], v[20:21], 0, s[10:11]
	v_pk_mul_f32 v[2:3], v[28:29], v[30:31] op_sel_hi:[1,0]
	s_waitcnt vmcnt(3)
	v_lshlrev_b32_e32 v28, 16, v48
	s_waitcnt vmcnt(2)
	v_lshlrev_b32_e32 v29, 16, v51
	v_lshlrev_b32_e32 v5, 16, v49
	v_lshlrev_b32_e32 v4, 16, v50
	v_pk_mul_f32 v[28:29], v[2:3], v[28:29] op_sel:[1,0] op_sel_hi:[0,1]
	v_pk_fma_f32 v[4:5], v[2:3], v[4:5], v[28:29]
	s_waitcnt vmcnt(1)
	v_lshlrev_b32_e32 v29, 16, v53
	v_lshlrev_b32_e32 v28, 16, v52
	v_and_b32_e32 v31, 0xffff0000, v51
	v_and_b32_e32 v30, 0xffff0000, v48
	v_pk_fma_f32 v[4:5], v[40:41], v[28:29], v[4:5] op_sel_hi:[0,1,1]
	v_and_b32_e32 v29, 0xffff0000, v49
	v_and_b32_e32 v28, 0xffff0000, v50
	v_pk_mul_f32 v[30:31], v[2:3], v[30:31] op_sel:[1,0] op_sel_hi:[0,1]
	v_pk_fma_f32 v[2:3], v[2:3], v[28:29], v[30:31]
	v_and_b32_e32 v29, 0xffff0000, v53
	v_and_b32_e32 v28, 0xffff0000, v52
	v_pk_fma_f32 v[2:3], v[40:41], v[28:29], v[2:3] op_sel_hi:[0,1,1]
	v_and_b32_sdwa v27, v5, v243 dst_sel:DWORD dst_unused:UNUSED_PAD src0_sel:WORD_1 src1_sel:DWORD
	v_and_b32_sdwa v28, v4, v243 dst_sel:DWORD dst_unused:UNUSED_PAD src0_sel:WORD_1 src1_sel:DWORD
	v_add3_u32 v4, v4, v28, s68
	v_add3_u32 v5, v5, v27, s68
	v_and_b32_sdwa v27, v3, v243 dst_sel:DWORD dst_unused:UNUSED_PAD src0_sel:WORD_1 src1_sel:DWORD
	v_and_b32_sdwa v28, v2, v243 dst_sel:DWORD dst_unused:UNUSED_PAD src0_sel:WORD_1 src1_sel:DWORD
	v_add3_u32 v3, v3, v27, s68
	v_add3_u32 v2, v2, v28, s68
	v_and_b32_e32 v3, 0xffff0000, v3
	v_and_b32_e32 v2, 0xffff0000, v2
	v_or_b32_sdwa v3, v3, v5 dst_sel:DWORD dst_unused:UNUSED_PAD src0_sel:DWORD src1_sel:WORD_1
	v_or_b32_sdwa v2, v2, v4 dst_sel:DWORD dst_unused:UNUSED_PAD src0_sel:DWORD src1_sel:WORD_1
	global_store_dwordx2 v[60:61], v[2:3], off offset:-1536
	s_cbranch_scc0 .LBB0_200
	s_mov_b64 s[36:37], s[72:73]

.LBB0_228:
	v_exp_f32_e32 v116, v116
	v_exp_f32_e32 v117, v117
	v_add_f32_e32 v224, v224, v116
	v_cvt_pk_bf16_f32 v175, v116, v117
	v_add_f32_e32 v225, v225, v117
	s_waitcnt lgkmcnt(4)
	v_mfma_f32_32x32x16_bf16 v[98:113], v[182:185], v[154:157], v[98:113]
	ds_read_b128 v[130:133], v254 offset:4096
	ds_read_b128 v[134:137], v254 offset:4608
	v_exp_f32_e32 v118, v118
	v_exp_f32_e32 v119, v119
	v_add_f32_e32 v224, v224, v118
	v_cvt_pk_bf16_f32 v176, v118, v119
	v_add_f32_e32 v225, v225, v119
	s_waitcnt lgkmcnt(5)
	v_mfma_f32_32x32x16_bf16 v[66:81], v[178:181], v[154:157], v[66:81]
	v_exp_f32_e32 v120, v120
	v_exp_f32_e32 v121, v121
	v_add_f32_e32 v224, v224, v120
	v_cvt_pk_bf16_f32 v177, v120, v121
	v_add_f32_e32 v225, v225, v121
	s_waitcnt lgkmcnt(1)
	v_mfma_f32_32x32x16_bf16 v[98:113], v[130:133], v[150:153], v[98:113]
	ds_read_b128 v[138:141], v254 offset:6144
	ds_read_b128 v[142:145], v254 offset:6656
	v_exp_f32_e32 v122, v122
	v_exp_f32_e32 v123, v123
	v_add_f32_e32 v224, v224, v122
	v_cvt_pk_bf16_f32 v130, v122, v123
	v_add_f32_e32 v225, v225, v123
	s_waitcnt lgkmcnt(2)
	v_mfma_f32_32x32x16_bf16 v[66:81], v[134:137], v[150:153], v[66:81]
	v_exp_f32_e32 v124, v124
	v_exp_f32_e32 v125, v125
	v_add_f32_e32 v224, v224, v124
	v_cvt_pk_bf16_f32 v131, v124, v125
	v_add_f32_e32 v225, v225, v125
	s_waitcnt lgkmcnt(1)
	v_mfma_f32_32x32x16_bf16 v[98:113], v[138:141], v[146:149], v[98:113]
	v_exp_f32_e32 v126, v126
	v_exp_f32_e32 v127, v127
	v_add_f32_e32 v224, v224, v126
	v_cvt_pk_bf16_f32 v132, v126, v127
	v_add_f32_e32 v225, v225, v127
	s_waitcnt lgkmcnt(0)
	v_mfma_f32_32x32x16_bf16 v[66:81], v[142:145], v[146:149], v[66:81]
	v_exp_f32_e32 v128, v128
	v_exp_f32_e32 v129, v129
	v_add_f32_e32 v224, v224, v128
	v_cvt_pk_bf16_f32 v133, v128, v129
	v_add_f32_e32 v225, v225, v129
	ds_read_b64_tr_b16 v[134:135], v243 offset:40960
	ds_read_b64_tr_b16 v[136:137], v243 offset:41472
	ds_read_b64_tr_b16 v[138:139], v243 offset:45056
	ds_read_b64_tr_b16 v[140:141], v243 offset:45568
	s_waitcnt lgkmcnt(2)
	v_mfma_f32_32x32x16_bf16 v[50:65], v[174:177], v[134:137], v[50:65]
	ds_read_b64_tr_b16 v[142:143], v243 offset:49152
	ds_read_b64_tr_b16 v[144:145], v243 offset:49664
	v_exp_f32_e32 v82, v82
	v_exp_f32_e32 v83, v83
	v_add_f32_e32 v224, v224, v82
	v_cvt_pk_bf16_f32 v114, v82, v83
	v_add_f32_e32 v225, v225, v83
	s_waitcnt lgkmcnt(2)
	v_mfma_f32_32x32x16_bf16 v[34:49], v[174:177], v[138:141], v[34:49]
	ds_read_b64_tr_b16 v[134:135], v243 offset:53248
	ds_read_b64_tr_b16 v[136:137], v243 offset:53760
	v_exp_f32_e32 v84, v84
	v_exp_f32_e32 v85, v85
	v_add_f32_e32 v224, v224, v84
	v_cvt_pk_bf16_f32 v115, v84, v85
	v_add_f32_e32 v225, v225, v85
	s_waitcnt lgkmcnt(2)
	v_mfma_f32_32x32x16_bf16 v[18:33], v[174:177], v[142:145], v[18:33]
	ds_read_b64_tr_b16 v[138:139], v243 offset:41984
	ds_read_b64_tr_b16 v[140:141], v243 offset:42496
	v_exp_f32_e32 v86, v86
	v_exp_f32_e32 v87, v87
	v_add_f32_e32 v224, v224, v86
	v_cvt_pk_bf16_f32 v116, v86, v87
	v_add_f32_e32 v225, v225, v87
	s_waitcnt lgkmcnt(2)
	v_mfma_f32_32x32x16_bf16 v[2:17], v[174:177], v[134:137], v[2:17]
	ds_read_b64_tr_b16 v[142:143], v243 offset:46080
	ds_read_b64_tr_b16 v[144:145], v243 offset:46592
	v_exp_f32_e32 v88, v88
	v_exp_f32_e32 v89, v89
	v_add_f32_e32 v224, v224, v88
	v_cvt_pk_bf16_f32 v117, v88, v89
	v_add_f32_e32 v225, v225, v89
	s_waitcnt lgkmcnt(2)
	v_mfma_f32_32x32x16_bf16 v[50:65], v[130:133], v[138:141], v[50:65]
	ds_read_b64_tr_b16 v[134:135], v243 offset:50176
	ds_read_b64_tr_b16 v[136:137], v243 offset:50688
	v_exp_f32_e32 v90, v90
	v_exp_f32_e32 v91, v91
	v_add_f32_e32 v224, v224, v90
	v_cvt_pk_bf16_f32 v118, v90, v91
	v_add_f32_e32 v225, v225, v91
	s_waitcnt lgkmcnt(2)
	v_mfma_f32_32x32x16_bf16 v[34:49], v[130:133], v[142:145], v[34:49]
	ds_read_b64_tr_b16 v[138:139], v243 offset:54272
	ds_read_b64_tr_b16 v[140:141], v243 offset:54784
	v_exp_f32_e32 v92, v92
	v_exp_f32_e32 v93, v93
	v_add_f32_e32 v224, v224, v92
	v_cvt_pk_bf16_f32 v119, v92, v93
	v_add_f32_e32 v225, v225, v93
	s_waitcnt lgkmcnt(2)
	v_mfma_f32_32x32x16_bf16 v[18:33], v[130:133], v[134:137], v[18:33]
	ds_read_b64_tr_b16 v[142:143], v243 offset:43008
	ds_read_b64_tr_b16 v[144:145], v243 offset:43520
	v_exp_f32_e32 v94, v94
	v_exp_f32_e32 v95, v95
	v_add_f32_e32 v224, v224, v94
	v_cvt_pk_bf16_f32 v120, v94, v95
	v_add_f32_e32 v225, v225, v95
	s_waitcnt lgkmcnt(2)
	v_mfma_f32_32x32x16_bf16 v[2:17], v[130:133], v[138:141], v[2:17]
	ds_read_b64_tr_b16 v[134:135], v243 offset:47104
	ds_read_b64_tr_b16 v[136:137], v243 offset:47616
	v_exp_f32_e32 v96, v96
	v_exp_f32_e32 v97, v97
	v_add_f32_e32 v224, v224, v96
	v_cvt_pk_bf16_f32 v121, v96, v97
	v_add_f32_e32 v225, v225, v97
	s_waitcnt lgkmcnt(2)
	v_mfma_f32_32x32x16_bf16 v[50:65], v[114:117], v[142:145], v[50:65]
	ds_read_b64_tr_b16 v[128:129], v243 offset:51200
	ds_read_b64_tr_b16 v[130:131], v243 offset:51712
	v_max_f32_e32 v0, v98, v98
	v_max_f32_e32 v0, 0xf149f2ca, v0
	v_max3_f32 v174, v66, s25, v67
	s_waitcnt lgkmcnt(2)
	v_mfma_f32_32x32x16_bf16 v[34:49], v[114:117], v[134:137], v[34:49]
	ds_read_b64_tr_b16 v[138:139], v243 offset:55296
	ds_read_b64_tr_b16 v[140:141], v243 offset:55808
	v_max3_f32 v0, v0, v99, v100
	v_max3_f32 v174, v174, v68, v69
	s_waitcnt lgkmcnt(2)
	v_mfma_f32_32x32x16_bf16 v[18:33], v[114:117], v[128:131], v[18:33]
	ds_read_b64_tr_b16 v[132:133], v243 offset:44032
	ds_read_b64_tr_b16 v[134:135], v243 offset:44544
	v_max3_f32 v0, v0, v101, v102
	v_max3_f32 v174, v174, v70, v71
	s_waitcnt lgkmcnt(2)
	v_mfma_f32_32x32x16_bf16 v[2:17], v[114:117], v[138:141], v[2:17]
	ds_read_b64_tr_b16 v[128:129], v243 offset:48128
	ds_read_b64_tr_b16 v[130:131], v243 offset:48640
	v_max3_f32 v0, v0, v103, v104
	v_max3_f32 v174, v174, v72, v73
	s_waitcnt lgkmcnt(2)
	v_mfma_f32_32x32x16_bf16 v[50:65], v[118:121], v[132:135], v[50:65]
	ds_read_b64_tr_b16 v[114:115], v243 offset:52224
	ds_read_b64_tr_b16 v[116:117], v243 offset:52736
	v_max3_f32 v0, v0, v105, v106
	v_max3_f32 v174, v174, v74, v75
	s_waitcnt lgkmcnt(2)
	v_mfma_f32_32x32x16_bf16 v[34:49], v[118:121], v[128:131], v[34:49]
	ds_read_b64_tr_b16 v[132:133], v243 offset:56320
	ds_read_b64_tr_b16 v[134:135], v243 offset:56832
	v_max3_f32 v0, v0, v107, v108
	v_max3_f32 v174, v174, v76, v77
	s_waitcnt lgkmcnt(2)
	v_mfma_f32_32x32x16_bf16 v[18:33], v[118:121], v[114:117], v[18:33]
	v_max3_f32 v0, v0, v109, v110
	v_max3_f32 v174, v174, v78, v79
	s_waitcnt lgkmcnt(0)
	v_mfma_f32_32x32x16_bf16 v[2:17], v[118:121], v[132:135], v[2:17]
	v_max3_f32 v0, v0, v111, v112
	v_max3_f32 v174, v174, v80, v81
	s_add_i32 s36, s36, 2
	v_max3_f32 v114, v0, v113, v174
	v_lshl_add_u64 v[218:219], v[218:219], 0, s[42:43]
	v_lshl_add_u64 v[220:221], v[220:221], 0, s[42:43]
	s_cmpk_gt_u32 s36, 0x7d
	v_lshl_add_u64 v[222:223], v[222:223], 0, s[42:43]
	s_barrier
	s_cbranch_scc1 .LBB0_255

.LBB0_241:
	v_exp_f32_e32 v100, v100
	v_exp_f32_e32 v101, v101
	v_add_f32_e32 v224, v224, v100
	v_cvt_pk_bf16_f32 v175, v100, v101
	v_add_f32_e32 v225, v225, v101
	s_waitcnt lgkmcnt(4)
	v_mfma_f32_32x32x16_bf16 v[114:129], v[182:185], v[154:157], v[114:129]
	ds_read_b128 v[130:133], v254 offset:16384
	ds_read_b128 v[134:137], v254 offset:16896
	v_exp_f32_e32 v102, v102
	v_exp_f32_e32 v103, v103
	v_add_f32_e32 v224, v224, v102
	v_cvt_pk_bf16_f32 v176, v102, v103
	v_add_f32_e32 v225, v225, v103
	s_waitcnt lgkmcnt(5)
	v_mfma_f32_32x32x16_bf16 v[82:97], v[178:181], v[154:157], v[82:97]
	v_exp_f32_e32 v104, v104
	v_exp_f32_e32 v105, v105
	v_add_f32_e32 v224, v224, v104
	v_cvt_pk_bf16_f32 v177, v104, v105
	v_add_f32_e32 v225, v225, v105
	s_waitcnt lgkmcnt(1)
	v_mfma_f32_32x32x16_bf16 v[114:129], v[130:133], v[150:153], v[114:129]
	ds_read_b128 v[138:141], v254 offset:18432
	ds_read_b128 v[142:145], v254 offset:18944
	v_exp_f32_e32 v106, v106
	v_exp_f32_e32 v107, v107
	v_add_f32_e32 v224, v224, v106
	v_cvt_pk_bf16_f32 v130, v106, v107
	v_add_f32_e32 v225, v225, v107
	s_waitcnt lgkmcnt(2)
	v_mfma_f32_32x32x16_bf16 v[82:97], v[134:137], v[150:153], v[82:97]
	v_exp_f32_e32 v108, v108
	v_exp_f32_e32 v109, v109
	v_add_f32_e32 v224, v224, v108
	v_cvt_pk_bf16_f32 v131, v108, v109
	v_add_f32_e32 v225, v225, v109
	s_waitcnt lgkmcnt(1)
	v_mfma_f32_32x32x16_bf16 v[114:129], v[138:141], v[146:149], v[114:129]
	v_exp_f32_e32 v110, v110
	v_exp_f32_e32 v111, v111
	v_add_f32_e32 v224, v224, v110
	v_cvt_pk_bf16_f32 v132, v110, v111
	v_add_f32_e32 v225, v225, v111
	s_waitcnt lgkmcnt(0)
	v_mfma_f32_32x32x16_bf16 v[82:97], v[142:145], v[146:149], v[82:97]
	v_exp_f32_e32 v112, v112
	v_exp_f32_e32 v113, v113
	v_add_f32_e32 v224, v224, v112
	v_cvt_pk_bf16_f32 v133, v112, v113
	v_add_f32_e32 v225, v225, v113
	ds_read_b64_tr_b16 v[134:135], v243 offset:24576
	ds_read_b64_tr_b16 v[136:137], v243 offset:25088
	ds_read_b64_tr_b16 v[138:139], v243 offset:28672
	ds_read_b64_tr_b16 v[140:141], v243 offset:29184
	s_waitcnt lgkmcnt(2)
	v_mfma_f32_32x32x16_bf16 v[50:65], v[174:177], v[134:137], v[50:65]
	ds_read_b64_tr_b16 v[142:143], v243 offset:32768
	ds_read_b64_tr_b16 v[144:145], v243 offset:33280
	v_exp_f32_e32 v66, v66
	v_exp_f32_e32 v67, v67
	v_add_f32_e32 v224, v224, v66
	v_cvt_pk_bf16_f32 v98, v66, v67
	v_add_f32_e32 v225, v225, v67
	s_waitcnt lgkmcnt(2)
	v_mfma_f32_32x32x16_bf16 v[34:49], v[174:177], v[138:141], v[34:49]
	ds_read_b64_tr_b16 v[134:135], v243 offset:36864
	ds_read_b64_tr_b16 v[136:137], v243 offset:37376
	v_exp_f32_e32 v68, v68
	v_exp_f32_e32 v69, v69
	v_add_f32_e32 v224, v224, v68
	v_cvt_pk_bf16_f32 v99, v68, v69
	v_add_f32_e32 v225, v225, v69
	s_waitcnt lgkmcnt(2)
	v_mfma_f32_32x32x16_bf16 v[18:33], v[174:177], v[142:145], v[18:33]
	ds_read_b64_tr_b16 v[138:139], v243 offset:25600
	ds_read_b64_tr_b16 v[140:141], v243 offset:26112
	v_exp_f32_e32 v70, v70
	v_exp_f32_e32 v71, v71
	v_add_f32_e32 v224, v224, v70
	v_cvt_pk_bf16_f32 v100, v70, v71
	v_add_f32_e32 v225, v225, v71
	s_waitcnt lgkmcnt(2)
	v_mfma_f32_32x32x16_bf16 v[2:17], v[174:177], v[134:137], v[2:17]
	ds_read_b64_tr_b16 v[142:143], v243 offset:29696
	ds_read_b64_tr_b16 v[144:145], v243 offset:30208
	v_exp_f32_e32 v72, v72
	v_exp_f32_e32 v73, v73
	v_add_f32_e32 v224, v224, v72
	v_cvt_pk_bf16_f32 v101, v72, v73
	v_add_f32_e32 v225, v225, v73
	s_waitcnt lgkmcnt(2)
	v_mfma_f32_32x32x16_bf16 v[50:65], v[130:133], v[138:141], v[50:65]
	ds_read_b64_tr_b16 v[134:135], v243 offset:33792
	ds_read_b64_tr_b16 v[136:137], v243 offset:34304
	v_exp_f32_e32 v74, v74
	v_exp_f32_e32 v75, v75
	v_add_f32_e32 v224, v224, v74
	v_cvt_pk_bf16_f32 v102, v74, v75
	v_add_f32_e32 v225, v225, v75
	s_waitcnt lgkmcnt(2)
	v_mfma_f32_32x32x16_bf16 v[34:49], v[130:133], v[142:145], v[34:49]
	ds_read_b64_tr_b16 v[138:139], v243 offset:37888
	ds_read_b64_tr_b16 v[140:141], v243 offset:38400
	v_exp_f32_e32 v76, v76
	v_exp_f32_e32 v77, v77
	v_add_f32_e32 v224, v224, v76
	v_cvt_pk_bf16_f32 v103, v76, v77
	v_add_f32_e32 v225, v225, v77
	s_waitcnt lgkmcnt(2)
	v_mfma_f32_32x32x16_bf16 v[18:33], v[130:133], v[134:137], v[18:33]
	ds_read_b64_tr_b16 v[142:143], v243 offset:26624
	ds_read_b64_tr_b16 v[144:145], v243 offset:27136
	v_exp_f32_e32 v78, v78
	v_exp_f32_e32 v79, v79
	v_add_f32_e32 v224, v224, v78
	v_cvt_pk_bf16_f32 v104, v78, v79
	v_add_f32_e32 v225, v225, v79
	s_waitcnt lgkmcnt(2)
	v_mfma_f32_32x32x16_bf16 v[2:17], v[130:133], v[138:141], v[2:17]
	ds_read_b64_tr_b16 v[134:135], v243 offset:30720
	ds_read_b64_tr_b16 v[136:137], v243 offset:31232
	v_exp_f32_e32 v80, v80
	v_exp_f32_e32 v81, v81
	v_add_f32_e32 v224, v224, v80
	v_cvt_pk_bf16_f32 v105, v80, v81
	v_add_f32_e32 v225, v225, v81
	s_waitcnt lgkmcnt(2)
	v_mfma_f32_32x32x16_bf16 v[50:65], v[98:101], v[142:145], v[50:65]
	ds_read_b64_tr_b16 v[130:131], v243 offset:34816
	ds_read_b64_tr_b16 v[132:133], v243 offset:35328
	v_max_f32_e32 v0, v114, v114
	v_max_f32_e32 v0, 0xf149f2ca, v0
	v_max3_f32 v112, v82, s25, v83
	s_waitcnt lgkmcnt(2)
	v_mfma_f32_32x32x16_bf16 v[34:49], v[98:101], v[134:137], v[34:49]
	ds_read_b64_tr_b16 v[138:139], v243 offset:38912
	ds_read_b64_tr_b16 v[140:141], v243 offset:39424
	v_max3_f32 v0, v0, v115, v116
	v_max3_f32 v112, v112, v84, v85
	s_waitcnt lgkmcnt(2)
	v_mfma_f32_32x32x16_bf16 v[18:33], v[98:101], v[130:133], v[18:33]
	ds_read_b64_tr_b16 v[134:135], v243 offset:27648
	ds_read_b64_tr_b16 v[136:137], v243 offset:28160
	v_max3_f32 v0, v0, v117, v118
	v_max3_f32 v112, v112, v86, v87
	s_waitcnt lgkmcnt(2)
	v_mfma_f32_32x32x16_bf16 v[2:17], v[98:101], v[138:141], v[2:17]
	ds_read_b64_tr_b16 v[130:131], v243 offset:31744
	ds_read_b64_tr_b16 v[132:133], v243 offset:32256
	v_max3_f32 v0, v0, v119, v120
	v_max3_f32 v112, v112, v88, v89
	s_waitcnt lgkmcnt(2)
	v_mfma_f32_32x32x16_bf16 v[50:65], v[102:105], v[134:137], v[50:65]
	ds_read_b64_tr_b16 v[98:99], v243 offset:35840
	ds_read_b64_tr_b16 v[100:101], v243 offset:36352
	v_max3_f32 v0, v0, v121, v122
	v_max3_f32 v112, v112, v90, v91
	s_waitcnt lgkmcnt(2)
	v_mfma_f32_32x32x16_bf16 v[34:49], v[102:105], v[130:133], v[34:49]
	ds_read_b64_tr_b16 v[134:135], v243 offset:39936
	ds_read_b64_tr_b16 v[136:137], v243 offset:40448
	v_max3_f32 v0, v0, v123, v124
	v_max3_f32 v112, v112, v92, v93
	s_waitcnt lgkmcnt(2)
	v_mfma_f32_32x32x16_bf16 v[18:33], v[102:105], v[98:101], v[18:33]
	v_max3_f32 v0, v0, v125, v126
	v_max3_f32 v112, v112, v94, v95
	s_waitcnt lgkmcnt(0)
	v_mfma_f32_32x32x16_bf16 v[2:17], v[102:105], v[134:137], v[2:17]
	v_max3_f32 v0, v0, v127, v128
	v_max3_f32 v112, v112, v96, v97
	v_max3_f32 v0, v0, v129, v112
	v_cmp_lt_f32_e32 vcc, s16, v0
	s_barrier
	s_cbranch_vccz .LBB0_245
	ds_bpermute_b32 v98, v251, v0
	s_waitcnt lgkmcnt(0)
	v_max3_f32 v98, v0, v98, 0
	v_exp_f32_e64 v0, -v98
	s_and_saveexec_b64 s[38:39], s[6:7]
	ds_write_b32 v209, v0 offset:57344
	s_or_b64 exec, exec, s[38:39]
	v_sub_f32_e32 v129, v129, v98
	v_sub_f32_e32 v128, v128, v98
	v_sub_f32_e32 v127, v127, v98
	v_sub_f32_e32 v126, v126, v98
	v_sub_f32_e32 v125, v125, v98
	v_sub_f32_e32 v124, v124, v98
	v_sub_f32_e32 v123, v123, v98
	v_sub_f32_e32 v122, v122, v98
	v_sub_f32_e32 v121, v121, v98
	v_sub_f32_e32 v120, v120, v98
	v_sub_f32_e32 v119, v119, v98
	v_sub_f32_e32 v118, v118, v98
	v_sub_f32_e32 v117, v117, v98
	v_sub_f32_e32 v116, v116, v98
	v_sub_f32_e32 v115, v115, v98
	v_sub_f32_e32 v114, v114, v98
	v_sub_f32_e32 v82, v82, v98
	v_sub_f32_e32 v83, v83, v98
	v_sub_f32_e32 v84, v84, v98
	v_sub_f32_e32 v85, v85, v98
	v_sub_f32_e32 v86, v86, v98
	v_sub_f32_e32 v87, v87, v98
	v_sub_f32_e32 v88, v88, v98
	v_sub_f32_e32 v89, v89, v98
	v_sub_f32_e32 v90, v90, v98
	v_sub_f32_e32 v91, v91, v98
	v_sub_f32_e32 v92, v92, v98
	v_sub_f32_e32 v93, v93, v98
	v_sub_f32_e32 v94, v94, v98
	v_sub_f32_e32 v95, v95, v98
	v_sub_f32_e32 v96, v96, v98
	v_sub_f32_e32 v97, v97, v98
	v_add_f32_e32 v236, v236, v98
	ds_read_b128 v[98:101], v207 offset:57344
	ds_read_b128 v[102:105], v207 offset:57376
	ds_read_b128 v[106:109], v207 offset:57408
	ds_read_b128 v[110:113], v207 offset:57440
	v_pk_mul_f32 v[224:225], v[224:225], v[0:1] op_sel_hi:[1,0]
	s_waitcnt lgkmcnt(3)
	v_pk_mul_f32 v[52:53], v[52:53], v[100:101]
	s_waitcnt lgkmcnt(2)
	v_pk_mul_f32 v[56:57], v[56:57], v[104:105]
	s_waitcnt lgkmcnt(1)
	v_pk_mul_f32 v[60:61], v[60:61], v[108:109]
	s_waitcnt lgkmcnt(0)
	v_pk_mul_f32 v[64:65], v[64:65], v[112:113]
	v_pk_mul_f32 v[62:63], v[62:63], v[110:111]
	v_pk_mul_f32 v[58:59], v[58:59], v[106:107]
	v_pk_mul_f32 v[54:55], v[54:55], v[102:103]
	v_pk_mul_f32 v[50:51], v[50:51], v[98:99]
	v_pk_mul_f32 v[48:49], v[48:49], v[112:113]
	v_pk_mul_f32 v[44:45], v[44:45], v[108:109]
	v_pk_mul_f32 v[40:41], v[40:41], v[104:105]
	v_pk_mul_f32 v[36:37], v[36:37], v[100:101]
	v_pk_mul_f32 v[46:47], v[46:47], v[110:111]
	v_pk_mul_f32 v[42:43], v[42:43], v[106:107]
	v_pk_mul_f32 v[38:39], v[38:39], v[102:103]
	v_pk_mul_f32 v[34:35], v[34:35], v[98:99]
	v_pk_mul_f32 v[32:33], v[32:33], v[112:113]
	v_pk_mul_f32 v[28:29], v[28:29], v[108:109]
	v_pk_mul_f32 v[24:25], v[24:25], v[104:105]
	v_pk_mul_f32 v[20:21], v[20:21], v[100:101]
	v_pk_mul_f32 v[30:31], v[30:31], v[110:111]
	v_pk_mul_f32 v[26:27], v[26:27], v[106:107]
	v_pk_mul_f32 v[22:23], v[22:23], v[102:103]
	v_pk_mul_f32 v[18:19], v[18:19], v[98:99]
	v_pk_mul_f32 v[16:17], v[16:17], v[112:113]
	v_pk_mul_f32 v[12:13], v[12:13], v[108:109]
	v_pk_mul_f32 v[8:9], v[8:9], v[104:105]
	v_pk_mul_f32 v[4:5], v[4:5], v[100:101]
	v_pk_mul_f32 v[14:15], v[14:15], v[110:111]
	v_pk_mul_f32 v[10:11], v[10:11], v[106:107]
	v_pk_mul_f32 v[6:7], v[6:7], v[102:103]
	v_pk_mul_f32 v[2:3], v[2:3], v[98:99]

.LBB0_287:
	v_lshl_add_u64 v[50:51], s[80:81], 0, v[222:223]
	global_load_dwordx4 v[178:181], v[50:51], off
	s_waitcnt lgkmcnt(3)
	v_mfma_f32_32x32x16_bf16 v[50:65], v[68:71], v[166:169], v[34:49]
	v_exp_f32_e32 v72, v114
	v_exp_f32_e32 v73, v115
	ds_read_b128 v[90:93], v254 offset:2048
	ds_read_b128 v[94:97], v254 offset:2560
	v_exp_f32_e32 v74, v130
	v_exp_f32_e32 v75, v131
	v_pk_add_f32 v[66:67], v[66:67], v[72:73]
	v_cvt_pk_bf16_f32 v114, v72, v73
	v_cvt_pk_bf16_f32 v84, v74, v75
	s_nop 0
	v_pk_add_f32 v[130:131], v[74:75], v[66:67]
	s_waitcnt lgkmcnt(4)
	v_mfma_f32_32x32x16_bf16 v[66:81], v[86:89], v[166:169], v[34:49]
	v_exp_f32_e32 v86, v116
	v_exp_f32_e32 v87, v117
	v_exp_f32_e32 v88, v132
	v_exp_f32_e32 v89, v133
	v_cvt_pk_bf16_f32 v115, v86, v87
	v_pk_add_f32 v[116:117], v[86:87], v[130:131]
	v_cvt_pk_bf16_f32 v85, v88, v89
	s_nop 0
	v_pk_add_f32 v[116:117], v[88:89], v[116:117]
	s_waitcnt lgkmcnt(1)
	v_mfma_f32_32x32x16_bf16 v[50:65], v[90:93], v[162:165], v[50:65]
	ds_read_b128 v[130:133], v254 offset:4096
	ds_read_b128 v[190:193], v254 offset:4608
	v_exp_f32_e32 v86, v118
	v_exp_f32_e32 v87, v119
	v_exp_f32_e32 v88, v134
	v_exp_f32_e32 v89, v135
	v_pk_add_f32 v[90:91], v[86:87], v[116:117]
	v_cvt_pk_bf16_f32 v116, v86, v87
	s_nop 0
	v_pk_add_f32 v[90:91], v[88:89], v[90:91]
	v_cvt_pk_bf16_f32 v86, v88, v89
	s_waitcnt lgkmcnt(2)
	v_mfma_f32_32x32x16_bf16 v[66:81], v[94:97], v[162:165], v[66:81]
	v_exp_f32_e32 v88, v120
	v_exp_f32_e32 v89, v121
	v_exp_f32_e32 v92, v136
	v_exp_f32_e32 v93, v137
	v_cvt_pk_bf16_f32 v117, v88, v89
	v_pk_add_f32 v[90:91], v[88:89], v[90:91]
	v_cvt_pk_bf16_f32 v87, v92, v93
	s_nop 0
	v_pk_add_f32 v[96:97], v[92:93], v[90:91]
	s_waitcnt lgkmcnt(1)
	v_mfma_f32_32x32x16_bf16 v[50:65], v[130:133], v[158:161], v[50:65]
	ds_read_b128 v[88:91], v254 offset:6144
	ds_read_b128 v[92:95], v254 offset:6656
	v_exp_f32_e32 v118, v122
	v_exp_f32_e32 v119, v123
	v_exp_f32_e32 v120, v138
	v_exp_f32_e32 v121, v139
	v_pk_add_f32 v[96:97], v[118:119], v[96:97]
	v_cvt_pk_bf16_f32 v118, v118, v119
	s_nop 0
	v_pk_add_f32 v[96:97], v[120:121], v[96:97]
	v_cvt_pk_bf16_f32 v122, v120, v121
	s_waitcnt lgkmcnt(2)
	v_mfma_f32_32x32x16_bf16 v[66:81], v[190:193], v[158:161], v[66:81]
	v_exp_f32_e32 v120, v124
	v_exp_f32_e32 v121, v125
	v_exp_f32_e32 v124, v140
	v_exp_f32_e32 v125, v141
	v_cvt_pk_bf16_f32 v119, v120, v121
	v_pk_add_f32 v[96:97], v[120:121], v[96:97]
	v_cvt_pk_bf16_f32 v123, v124, v125
	s_nop 0
	v_pk_add_f32 v[96:97], v[124:125], v[96:97]
	s_waitcnt lgkmcnt(1)
	v_mfma_f32_32x32x16_bf16 v[50:65], v[88:91], v[154:157], v[50:65]
	ds_read_b128 v[132:135], v254 offset:8192
	ds_read_b128 v[136:139], v254 offset:8704
	v_exp_f32_e32 v88, v126
	v_exp_f32_e32 v89, v127
	v_exp_f32_e32 v90, v142
	v_exp_f32_e32 v91, v143
	v_cvt_pk_bf16_f32 v120, v88, v89
	v_pk_add_f32 v[96:97], v[88:89], v[96:97]
	v_cvt_pk_bf16_f32 v124, v90, v91
	s_nop 0
	v_pk_add_f32 v[96:97], v[90:91], v[96:97]
	s_waitcnt lgkmcnt(2)
	v_mfma_f32_32x32x16_bf16 v[66:81], v[92:95], v[154:157], v[66:81]
	v_exp_f32_e32 v88, v128
	v_exp_f32_e32 v89, v129
	v_exp_f32_e32 v90, v144
	v_exp_f32_e32 v91, v145
	v_cvt_pk_bf16_f32 v121, v88, v89
	v_pk_add_f32 v[92:93], v[88:89], v[96:97]
	v_cvt_pk_bf16_f32 v125, v90, v91
	s_nop 0
	v_pk_add_f32 v[130:131], v[90:91], v[92:93]
	s_waitcnt lgkmcnt(1)
	v_mfma_f32_32x32x16_bf16 v[50:65], v[132:135], v[150:153], v[50:65]
	ds_read_b128 v[88:91], v254 offset:10240
	ds_read_b128 v[92:95], v254 offset:10752
	s_waitcnt lgkmcnt(2)
	v_mfma_f32_32x32x16_bf16 v[66:81], v[136:139], v[150:153], v[66:81]
	s_waitcnt lgkmcnt(1)
	v_mfma_f32_32x32x16_bf16 v[50:65], v[88:91], v[146:149], v[50:65]
	s_waitcnt lgkmcnt(0)
	v_mfma_f32_32x32x16_bf16 v[66:81], v[92:95], v[146:149], v[66:81]
	ds_read_b64_tr_b16 v[88:89], v243 offset:40960
	ds_read_b64_tr_b16 v[90:91], v243 offset:41472
	ds_read_b64_tr_b16 v[92:93], v243 offset:45056
	ds_read_b64_tr_b16 v[94:95], v243 offset:45568
	s_waitcnt lgkmcnt(2)
	v_mfma_f32_32x32x16_bf16 v[18:33], v[114:117], v[88:91], v[18:33]
	ds_read_b64_tr_b16 v[126:127], v243 offset:41984
	ds_read_b64_tr_b16 v[128:129], v243 offset:42496
	s_nop 0
	v_max_f32_e32 v83, v50, v50
	v_max_f32_e32 v83, 0xf149f2ca, v83
	v_max3_f32 v96, v66, s25, v67
	s_waitcnt lgkmcnt(2)
	v_mfma_f32_32x32x16_bf16 v[2:17], v[114:117], v[92:95], v[2:17]
	ds_read_b64_tr_b16 v[88:89], v243 offset:46080
	ds_read_b64_tr_b16 v[90:91], v243 offset:46592
	v_max3_f32 v83, v83, v51, v52
	v_max3_f32 v96, v96, v68, v69
	s_waitcnt lgkmcnt(2)
	v_mfma_f32_32x32x16_bf16 v[18:33], v[118:121], v[126:129], v[18:33]
	ds_read_b64_tr_b16 v[92:93], v243 offset:43008
	ds_read_b64_tr_b16 v[94:95], v243 offset:43520
	v_max3_f32 v83, v83, v53, v54
	v_max3_f32 v96, v96, v70, v71
	s_waitcnt lgkmcnt(2)
	v_mfma_f32_32x32x16_bf16 v[2:17], v[118:121], v[88:91], v[2:17]
	ds_read_b64_tr_b16 v[114:115], v243 offset:47104
	ds_read_b64_tr_b16 v[116:117], v243 offset:47616
	v_max3_f32 v83, v83, v55, v56
	v_max3_f32 v96, v96, v72, v73
	s_waitcnt lgkmcnt(2)
	v_mfma_f32_32x32x16_bf16 v[18:33], v[84:87], v[92:95], v[18:33]
	ds_read_b64_tr_b16 v[88:89], v243 offset:44032
	ds_read_b64_tr_b16 v[90:91], v243 offset:44544
	v_max3_f32 v83, v83, v57, v58
	v_max3_f32 v96, v96, v74, v75
	s_waitcnt lgkmcnt(2)
	v_mfma_f32_32x32x16_bf16 v[2:17], v[84:87], v[114:117], v[2:17]
	ds_read_b64_tr_b16 v[92:93], v243 offset:48128
	ds_read_b64_tr_b16 v[94:95], v243 offset:48640
	s_waitcnt lgkmcnt(2)
	v_mfma_f32_32x32x16_bf16 v[18:33], v[122:125], v[88:91], v[18:33]
	s_waitcnt lgkmcnt(0)
	v_mfma_f32_32x32x16_bf16 v[2:17], v[122:125], v[92:95], v[2:17]
	v_max3_f32 v83, v83, v59, v60
	v_max3_f32 v84, v96, v76, v77
	v_max3_f32 v83, v83, v61, v62
	v_max3_f32 v84, v84, v78, v79
	v_max3_f32 v83, v83, v63, v64
	v_max3_f32 v84, v84, v80, v81
	s_add_i32 s36, s36, 2
	v_max3_f32 v83, v83, v65, v84
	v_lshl_add_u64 v[218:219], v[218:219], 0, s[38:39]
	v_lshl_add_u64 v[220:221], v[220:221], 0, s[82:83]
	v_lshl_add_u64 v[222:223], v[222:223], 0, s[82:83]
	s_cmpk_gt_u32 s36, 0x7d
	v_lshl_add_u64 v[224:225], v[224:225], 0, s[82:83]
	s_barrier
	s_cbranch_scc1 .LBB0_305

.LBB0_295:
	v_lshl_add_u64 v[114:115], s[80:81], 0, v[224:225]
	global_load_dwordx4 v[178:181], v[114:115], off
	s_waitcnt lgkmcnt(3)
	v_mfma_f32_32x32x16_bf16 v[114:129], v[84:87], v[166:169], v[34:49]
	ds_read_b128 v[92:95], v254 offset:14336
	ds_read_b128 v[190:193], v254 offset:14848
	v_exp_f32_e32 v50, v50
	v_exp_f32_e32 v51, v51
	v_exp_f32_e32 v66, v66
	v_exp_f32_e32 v67, v67
	v_pk_add_f32 v[84:85], v[130:131], v[50:51]
	s_nop 0
	v_pk_add_f32 v[86:87], v[66:67], v[84:85]
	v_cvt_pk_bf16_f32 v84, v50, v51
	v_cvt_pk_bf16_f32 v50, v66, v67
	s_waitcnt lgkmcnt(4)
	v_mfma_f32_32x32x16_bf16 v[130:145], v[88:91], v[166:169], v[34:49]
	v_exp_f32_e32 v52, v52
	v_exp_f32_e32 v53, v53
	v_exp_f32_e32 v66, v68
	v_exp_f32_e32 v67, v69
	v_cvt_pk_bf16_f32 v85, v52, v53
	v_pk_add_f32 v[68:69], v[52:53], v[86:87]
	v_cvt_pk_bf16_f32 v51, v66, v67
	s_nop 0
	v_pk_add_f32 v[86:87], v[66:67], v[68:69]
	s_waitcnt lgkmcnt(1)
	v_mfma_f32_32x32x16_bf16 v[114:129], v[92:95], v[162:165], v[114:129]
	ds_read_b128 v[66:69], v254 offset:16384
	ds_read_b128 v[88:91], v254 offset:16896
	v_exp_f32_e32 v52, v54
	v_exp_f32_e32 v53, v55
	v_exp_f32_e32 v54, v70
	v_exp_f32_e32 v55, v71
	v_pk_add_f32 v[70:71], v[52:53], v[86:87]
	v_cvt_pk_bf16_f32 v86, v52, v53
	s_nop 0
	v_pk_add_f32 v[70:71], v[54:55], v[70:71]
	v_cvt_pk_bf16_f32 v52, v54, v55
	s_waitcnt lgkmcnt(2)
	v_mfma_f32_32x32x16_bf16 v[130:145], v[190:193], v[162:165], v[130:145]
	v_exp_f32_e32 v54, v56
	v_exp_f32_e32 v55, v57
	v_exp_f32_e32 v56, v72
	v_exp_f32_e32 v57, v73
	v_cvt_pk_bf16_f32 v87, v54, v55
	v_pk_add_f32 v[70:71], v[54:55], v[70:71]
	v_cvt_pk_bf16_f32 v53, v56, v57
	s_nop 0
	v_pk_add_f32 v[92:93], v[56:57], v[70:71]
	s_waitcnt lgkmcnt(1)
	v_mfma_f32_32x32x16_bf16 v[114:129], v[66:69], v[158:161], v[114:129]
	ds_read_b128 v[54:57], v254 offset:18432
	ds_read_b128 v[70:73], v254 offset:18944
	v_exp_f32_e32 v58, v58
	v_exp_f32_e32 v59, v59
	v_exp_f32_e32 v66, v74
	v_exp_f32_e32 v67, v75
	v_pk_add_f32 v[68:69], v[58:59], v[92:93]
	v_cvt_pk_bf16_f32 v58, v58, v59
	s_nop 0
	v_pk_add_f32 v[68:69], v[66:67], v[68:69]
	v_cvt_pk_bf16_f32 v74, v66, v67
	s_waitcnt lgkmcnt(2)
	v_mfma_f32_32x32x16_bf16 v[130:145], v[88:91], v[158:161], v[130:145]
	v_exp_f32_e32 v60, v60
	v_exp_f32_e32 v61, v61
	v_exp_f32_e32 v66, v76
	v_exp_f32_e32 v67, v77
	v_cvt_pk_bf16_f32 v59, v60, v61
	v_pk_add_f32 v[68:69], v[60:61], v[68:69]
	v_cvt_pk_bf16_f32 v75, v66, v67
	s_nop 0
	v_pk_add_f32 v[68:69], v[66:67], v[68:69]
	s_waitcnt lgkmcnt(1)
	v_mfma_f32_32x32x16_bf16 v[114:129], v[54:57], v[154:157], v[114:129]
	ds_read_b128 v[88:91], v254 offset:20480
	ds_read_b128 v[92:95], v254 offset:20992
	v_exp_f32_e32 v54, v62
	v_exp_f32_e32 v55, v63
	v_exp_f32_e32 v56, v78
	v_exp_f32_e32 v57, v79
	v_pk_add_f32 v[60:61], v[54:55], v[68:69]
	s_nop 0
	v_pk_add_f32 v[62:63], v[56:57], v[60:61]
	v_cvt_pk_bf16_f32 v60, v54, v55
	v_cvt_pk_bf16_f32 v76, v56, v57
	s_waitcnt lgkmcnt(2)
	v_mfma_f32_32x32x16_bf16 v[130:145], v[70:73], v[154:157], v[130:145]
	v_exp_f32_e32 v54, v64
	v_exp_f32_e32 v55, v65
	v_exp_f32_e32 v56, v80
	v_exp_f32_e32 v57, v81
	v_cvt_pk_bf16_f32 v61, v54, v55
	v_pk_add_f32 v[62:63], v[54:55], v[62:63]
	v_cvt_pk_bf16_f32 v77, v56, v57
	s_nop 0
	v_pk_add_f32 v[66:67], v[56:57], v[62:63]
	s_waitcnt lgkmcnt(1)
	v_mfma_f32_32x32x16_bf16 v[114:129], v[88:91], v[150:153], v[114:129]
	ds_read_b128 v[54:57], v254 offset:22528
	ds_read_b128 v[62:65], v254 offset:23040
	s_waitcnt lgkmcnt(2)
	v_mfma_f32_32x32x16_bf16 v[130:145], v[92:95], v[150:153], v[130:145]
	s_waitcnt lgkmcnt(1)
	v_mfma_f32_32x32x16_bf16 v[114:129], v[54:57], v[146:149], v[114:129]
	s_waitcnt lgkmcnt(0)
	v_mfma_f32_32x32x16_bf16 v[130:145], v[62:65], v[146:149], v[130:145]
	ds_read_b64_tr_b16 v[54:55], v243 offset:24576
	ds_read_b64_tr_b16 v[56:57], v243 offset:25088
	ds_read_b64_tr_b16 v[62:63], v243 offset:28672
	ds_read_b64_tr_b16 v[64:65], v243 offset:29184
	s_waitcnt lgkmcnt(2)
	v_mfma_f32_32x32x16_bf16 v[18:33], v[84:87], v[54:57], v[18:33]
	ds_read_b64_tr_b16 v[68:69], v243 offset:25600
	ds_read_b64_tr_b16 v[70:71], v243 offset:26112
	s_nop 0
	v_max_f32_e32 v54, v114, v114
	v_max_f32_e32 v72, 0xf149f2ca, v54
	v_max3_f32 v73, v130, s25, v131
	s_waitcnt lgkmcnt(2)
	v_mfma_f32_32x32x16_bf16 v[2:17], v[84:87], v[62:65], v[2:17]
	ds_read_b64_tr_b16 v[54:55], v243 offset:29696
	ds_read_b64_tr_b16 v[56:57], v243 offset:30208
	v_max3_f32 v72, v72, v115, v116
	v_max3_f32 v73, v73, v132, v133
	s_waitcnt lgkmcnt(2)
	v_mfma_f32_32x32x16_bf16 v[18:33], v[58:61], v[68:71], v[18:33]
	ds_read_b64_tr_b16 v[62:63], v243 offset:26624
	ds_read_b64_tr_b16 v[64:65], v243 offset:27136
	v_max3_f32 v72, v72, v117, v118
	v_max3_f32 v73, v73, v134, v135
	s_waitcnt lgkmcnt(2)
	v_mfma_f32_32x32x16_bf16 v[2:17], v[58:61], v[54:57], v[2:17]
	ds_read_b64_tr_b16 v[68:69], v243 offset:30720
	ds_read_b64_tr_b16 v[70:71], v243 offset:31232
	v_max3_f32 v58, v72, v119, v120
	v_max3_f32 v59, v73, v136, v137
	s_waitcnt lgkmcnt(2)
	v_mfma_f32_32x32x16_bf16 v[18:33], v[50:53], v[62:65], v[18:33]
	ds_read_b64_tr_b16 v[54:55], v243 offset:27648
	ds_read_b64_tr_b16 v[56:57], v243 offset:28160
	v_max3_f32 v62, v58, v121, v122
	v_max3_f32 v63, v59, v138, v139
	s_waitcnt lgkmcnt(2)
	v_mfma_f32_32x32x16_bf16 v[2:17], v[50:53], v[68:71], v[2:17]
	ds_read_b64_tr_b16 v[58:59], v243 offset:31744
	ds_read_b64_tr_b16 v[60:61], v243 offset:32256
	s_waitcnt lgkmcnt(2)
	v_mfma_f32_32x32x16_bf16 v[18:33], v[74:77], v[54:57], v[18:33]
	s_waitcnt lgkmcnt(0)
	v_mfma_f32_32x32x16_bf16 v[2:17], v[74:77], v[58:61], v[2:17]
	v_max3_f32 v50, v63, v140, v141
	v_max3_f32 v50, v50, v142, v143
	v_max3_f32 v51, v62, v123, v124
	v_max3_f32 v51, v51, v125, v126
	v_max3_f32 v50, v50, v144, v145
	v_max3_f32 v51, v51, v127, v128
	v_max3_f32 v50, v51, v129, v50
	v_cmp_lt_f32_e32 vcc, s16, v50
	s_barrier
	s_cbranch_vccz .LBB0_299
	ds_bpermute_b32 v34, v251, v50
	s_waitcnt lgkmcnt(0)
	v_max3_f32 v35, v50, v34, 0
	v_exp_f32_e64 v34, -v35
	s_and_saveexec_b64 s[12:13], s[6:7]
	ds_write_b32 v209, v34 offset:57344
	s_or_b64 exec, exec, s[12:13]
	ds_read_b128 v[36:39], v207 offset:57408
	ds_read_b128 v[40:43], v207 offset:57440
	ds_read_b128 v[44:47], v207 offset:57344
	ds_read_b128 v[48:51], v207 offset:57376
	v_add_f32_e32 v229, v229, v35
	v_xor_b32_e32 v82, 0x80000000, v229
	v_mov_b32_e32 v83, v82
	v_sub_f32_e32 v129, v129, v35
	v_sub_f32_e32 v128, v128, v35
	v_sub_f32_e32 v127, v127, v35
	v_sub_f32_e32 v126, v126, v35
	v_sub_f32_e32 v125, v125, v35
	v_sub_f32_e32 v124, v124, v35
	v_sub_f32_e32 v123, v123, v35
	v_sub_f32_e32 v122, v122, v35
	v_sub_f32_e32 v121, v121, v35
	v_sub_f32_e32 v120, v120, v35
	v_sub_f32_e32 v119, v119, v35
	v_sub_f32_e32 v118, v118, v35
	v_sub_f32_e32 v117, v117, v35
	v_sub_f32_e32 v116, v116, v35
	v_sub_f32_e32 v115, v115, v35
	v_sub_f32_e32 v114, v114, v35
	v_sub_f32_e32 v145, v145, v35
	v_sub_f32_e32 v144, v144, v35
	v_sub_f32_e32 v143, v143, v35
	v_sub_f32_e32 v142, v142, v35
	v_sub_f32_e32 v141, v141, v35
	v_sub_f32_e32 v140, v140, v35
	v_sub_f32_e32 v139, v139, v35
	v_sub_f32_e32 v138, v138, v35
	v_sub_f32_e32 v137, v137, v35
	v_sub_f32_e32 v136, v136, v35
	v_sub_f32_e32 v135, v135, v35
	v_sub_f32_e32 v134, v134, v35
	v_sub_f32_e32 v133, v133, v35
	v_sub_f32_e32 v132, v132, v35
	v_sub_f32_e32 v131, v131, v35
	v_sub_f32_e32 v130, v130, v35
	v_pk_mul_f32 v[66:67], v[66:67], v[34:35] op_sel_hi:[1,0]
	s_waitcnt lgkmcnt(2)
	v_pk_mul_f32 v[32:33], v[32:33], v[42:43]
	v_pk_mul_f32 v[28:29], v[28:29], v[38:39]
	s_waitcnt lgkmcnt(1)
	v_pk_mul_f32 v[20:21], v[20:21], v[46:47]
	v_pk_mul_f32 v[30:31], v[30:31], v[40:41]
	v_pk_mul_f32 v[26:27], v[26:27], v[36:37]
	s_waitcnt lgkmcnt(0)
	v_pk_mul_f32 v[22:23], v[22:23], v[48:49]
	v_pk_mul_f32 v[18:19], v[18:19], v[44:45]
	v_pk_mul_f32 v[16:17], v[16:17], v[42:43]
	v_pk_mul_f32 v[12:13], v[12:13], v[38:39]
	v_pk_mul_f32 v[4:5], v[4:5], v[46:47]
	v_pk_mul_f32 v[14:15], v[14:15], v[40:41]
	v_pk_mul_f32 v[10:11], v[10:11], v[36:37]
	v_pk_mul_f32 v[6:7], v[6:7], v[48:49]
	v_pk_mul_f32 v[2:3], v[2:3], v[44:45]
	v_mov_b32_e32 v84, v82
	v_mov_b32_e32 v85, v82
	v_mov_b32_e32 v86, v82
	v_mov_b32_e32 v87, v82
	v_mov_b32_e32 v88, v82
	v_mov_b32_e32 v89, v82
	v_mov_b32_e32 v90, v82
	v_mov_b32_e32 v91, v82
	v_mov_b32_e32 v92, v82
	v_mov_b32_e32 v93, v82
	v_mov_b32_e32 v94, v82
	v_mov_b32_e32 v95, v82
	v_mov_b32_e32 v96, v82
	v_mov_b32_e32 v97, v82
	v_mov_b64_e32 v[34:35], v[82:83]
	v_pk_mul_f32 v[24:25], v[24:25], v[50:51]
	v_pk_mul_f32 v[8:9], v[8:9], v[50:51]
	v_mov_b32_e32 v112, v82
	v_mov_b32_e32 v111, v82
	v_mov_b32_e32 v110, v82
	v_mov_b32_e32 v109, v82
	v_mov_b32_e32 v108, v82
	v_mov_b32_e32 v107, v82
	v_mov_b32_e32 v106, v82
	v_mov_b32_e32 v105, v82
	v_mov_b32_e32 v104, v82
	v_mov_b32_e32 v103, v82
	v_mov_b32_e32 v102, v82
	v_mov_b32_e32 v101, v82
	v_mov_b32_e32 v100, v82
	v_mov_b32_e32 v99, v82
	v_mov_b32_e32 v98, v82
	v_mov_b64_e32 v[36:37], v[84:85]
	v_mov_b64_e32 v[38:39], v[86:87]
	v_mov_b64_e32 v[40:41], v[88:89]
	v_mov_b64_e32 v[42:43], v[90:91]
	v_mov_b64_e32 v[44:45], v[92:93]
	v_mov_b64_e32 v[46:47], v[94:95]
	v_mov_b64_e32 v[48:49], v[96:97]

;     __device__ __forceinline__ void operator()(const f32x4 (&acc)[2][2][4][2], const Unit& u, int wr, int wc, int fr, int fq) const {
;     ...
;                 const int row = row0 + ai * HALF + m * 16, pos = row & (SEQ - 1);
;                 bf16_t* rowp = P + (size_t)row * NIN + col0;
;                 const float rstd = rsqrtf(ssq_x[row] * (1.f / DM) + EPS);
;                 float ss = 0.f;
;                 f32x4 c4 = (f32x4){1.f, 1.f, 1.f, 1.f}, s4 = (f32x4){0.f, 0.f, 0.f, 0.f};
;                 if (type == 0) { const int a = 4 * (wc & 1) + fq; c4 = *(const f32x4*)(cos64 + pos * 32 + 4 * a); s4 = *(const f32x4*)(sin64 + pos * 32 + 4 * a); }
;                 else if (type == 4) { c4 = *(const f32x4*)(cos32 + pos * 16 + 4 * fq); s4 = *(const f32x4*)(sin32 + pos * 16 + 4 * fq); }
; #pragma unroll
;                 for (int bj = 0; bj < 2; ++bj) {
;                     f32x4 v0 = acc[ai][bj][m][0] * rstd, v1 = acc[ai][bj][m][1] * rstd;
;                     if (type == 0 || type == 4) { const f32x4 lo = v0 * c4 - v1 * s4, hi_ = v1 * c4 + v0 * s4; v0 = lo * qs; v1 = hi_ * qs; }
;                     else if (type == 2 || type == 3) { ss += (v0[0] * v0[0] + v0[1] * v0[1]) + (v0[2] * v0[2] + v0[3] * v0[3]) + (v1[0] * v1[0] + v1[1] * v1[1]) + (v1[2] * v1[2] + v1[3] * v1[3]); }
;                     else if (type == 5) { const float* bp = bgate + (col0 + bj * HALF - PC_GATE); const f32x4 b0 = *(const f32x4*)bp, b1 = *(const f32x4*)(bp + 4);
.LBB0_611:
	v_lshl_add_u32 v160, s10, 8, v178
	v_ashrrev_i32_e32 v161, 31, v160
	v_lshl_add_u64 v[164:165], v[160:161], 2, s[40:41]
	global_load_dword v202, v[164:165], off
	global_load_dword v203, v[164:165], off offset:64
	global_load_dword v204, v[164:165], off offset:128
	global_load_dword v205, v[164:165], off offset:192
	global_load_dword v206, v[164:165], off offset:512
	global_load_dword v207, v[164:165], off offset:576
	global_load_dword v208, v[164:165], off offset:640
	global_load_dword v209, v[164:165], off offset:704
	s_cmp_lg_u32 s45, 5
	s_cbranch_scc1 .Linp_nogate
	v_lshl_or_b32 v226, s12, 8, v180
	v_ashrrev_i32_e32 v227, 31, v226
	s_movk_i32 s0, 0xb000
	s_mov_b32 s1, -1
	v_lshl_add_u64 v[226:227], v[226:227], 2, v[146:147]
	v_lshl_add_u64 v[226:227], v[226:227], 0, s[0:1]
	global_load_dwordx4 v[210:213], v[226:227], off
	global_load_dwordx4 v[214:217], v[226:227], off offset:16
	global_load_dwordx4 v[218:221], v[226:227], off offset:512
	global_load_dwordx4 v[222:225], v[226:227], off offset:528
.Linp_nogate:
	s_cmp_lt_i32 s45, 4
	s_cbranch_scc1 .LBB0_614
	s_mov_b64 s[14:15], 0
	s_cmp_eq_u32 s45, 4
	s_mov_b64 s[10:11], 0
	s_cbranch_scc0 .LBB0_615
	s_mov_b64 s[10:11], -1
	s_branch .LBB0_615

;     __device__ __forceinline__ void operator()(const f32x4 (&acc)[2][2][4][2], const Unit& u, int wr, int wc, int fr, int fq) const {
;     ...
;         if (pn < 4) type = 0; else if (pn < 6) type = 1; else if (pn < 15) type = ((pn - 6) % 3 < 2) ? 0 : 1; else if (pn < 18) type = 2; else if (pn == 18) type = 3; else if (pn == 19) type = 4; else type = 5;
;         const int row0 = u.pm * BM + wr * 64 + fr, col0 = pn * BM + wc * 32 + 8 * fq;
;         const float qs = (pn < 2 || (pn >= 6 && pn < 15 && (pn - 6) % 3 == 0)) ? 0.125f * 1.4426950408889634f : 1.f;
; #pragma unroll
;         for (int ai = 0; ai < 2; ++ai)
; #pragma unroll
;             for (int m = 0; m < 4; ++m) {
;                 const int row = row0 + ai * HALF + m * 16, pos = row & (SEQ - 1);
;                 bf16_t* rowp = P + (size_t)row * NIN + col0;
;                 const float rstd = rsqrtf(ssq_x[row] * (1.f / DM) + EPS);
.LBB0_620:
	s_and_b32 s0, s45, 6
	s_cmp_eq_u32 s0, 2
	s_cselect_b64 s[14:15], -1, 0
	s_cmp_lg_u32 s0, 2
	s_waitcnt vmcnt(0)
	v_fmamk_f32 v0, v202, 0x3a800000, v235
	s_cselect_b64 s[86:87], -1, 0
	s_cmp_eq_u32 s45, 5
	s_cselect_b64 s[84:85], -1, 0
	s_cmp_lt_i32 s45, 4
	v_cmp_gt_f32_e64 s[10:11], s58, v0
	s_cbranch_scc1 .LBB0_622
	s_cmp_lg_u32 s45, 4
	s_mov_b64 s[60:61], -1
	s_cselect_b64 s[62:63], -1, 0
	s_cbranch_execz .LBB0_623
	s_branch .LBB0_624

;     __device__ __forceinline__ void operator()(const f32x4 (&acc)[2][2][4][2], const Unit& u, int wr, int wc, int fr, int fq) const {
;     ...
;                 const float rstd = rsqrtf(ssq_x[row] * (1.f / DM) + EPS);
;                 float ss = 0.f;
;                 f32x4 c4 = (f32x4){1.f, 1.f, 1.f, 1.f}, s4 = (f32x4){0.f, 0.f, 0.f, 0.f};
;                 if (type == 0) { const int a = 4 * (wc & 1) + fq; c4 = *(const f32x4*)(cos64 + pos * 32 + 4 * a); s4 = *(const f32x4*)(sin64 + pos * 32 + 4 * a); }
;                 else if (type == 4) { c4 = *(const f32x4*)(cos32 + pos * 16 + 4 * fq); s4 = *(const f32x4*)(sin32 + pos * 16 + 4 * fq); }
; #pragma unroll
;                 for (int bj = 0; bj < 2; ++bj) {
;                     f32x4 v0 = acc[ai][bj][m][0] * rstd, v1 = acc[ai][bj][m][1] * rstd;
;                     if (type == 0 || type == 4) { const f32x4 lo = v0 * c4 - v1 * s4, hi_ = v1 * c4 + v0 * s4; v0 = lo * qs; v1 = hi_ * qs; }
;                     else if (type == 2 || type == 3) { ss += (v0[0] * v0[0] + v0[1] * v0[1]) + (v0[2] * v0[2] + v0[3] * v0[3]) + (v1[0] * v1[0] + v1[1] * v1[1]) + (v1[2] * v1[2] + v1[3] * v1[3]); }
;                     else if (type == 5) { const float* bp = bgate + (col0 + bj * HALF - PC_GATE); const f32x4 b0 = *(const f32x4*)bp, b1 = *(const f32x4*)(bp + 4);
; #pragma unroll
;                         for (int e = 0; e < 4; ++e) { v0[e] = __builtin_amdgcn_rcpf(1.f + __builtin_amdgcn_exp2f(-1.4426950408889634f * (v0[e] + b0[e]))); v1[e] = __builtin_amdgcn_rcpf(1.f + __builtin_amdgcn_exp2f(-1.4426950408889634f * (v1[e] + b1[e]))); } }
.LBB0_624:
	v_mul_f32_e32 v163, 0x4b800000, v0
	v_cndmask_b32_e64 v0, v0, v163, s[10:11]
	v_rsq_f32_e32 v0, v0
	s_andn2_b64 vcc, exec, s[62:63]
	v_mul_f32_e32 v163, 0x45800000, v0
	v_cndmask_b32_e64 v166, v0, v163, s[10:11]
	v_pk_mul_f32 v[168:169], v[122:123], v[166:167] op_sel_hi:[1,0]
	v_lshl_or_b32 v122, s12, 8, v180
	v_pk_mul_f32 v[128:129], v[128:129], v[166:167] op_sel_hi:[1,0]
	v_pk_mul_f32 v[126:127], v[126:127], v[166:167] op_sel_hi:[1,0]
	v_pk_mul_f32 v[124:125], v[124:125], v[166:167] op_sel_hi:[1,0]
	v_ashrrev_i32_e32 v123, 31, v122
	s_cbranch_vccnz .LBB0_632
	s_and_b64 vcc, exec, s[86:87]
	s_cbranch_vccz .LBB0_629
	s_andn2_b64 vcc, exec, s[84:85]
	v_mov_b32_e32 v171, v125
	v_mov_b32_e32 v170, v124
	v_mov_b32_e32 v173, v169
	v_mov_b32_e32 v172, v168
	v_mov_b32_e32 v175, v129
	v_mov_b32_e32 v174, v128
	v_mov_b32_e32 v177, v127
	v_mov_b32_e32 v176, v126
	s_cbranch_vccnz .LBB0_628
	s_movk_i32 s0, 0xb000
	v_lshl_add_u64 v[170:171], v[122:123], 2, v[146:147]
	s_mov_b32 s1, -1
	v_lshl_add_u64 v[174:175], v[170:171], 0, s[0:1]
	v_add_co_u32_e32 v170, vcc, 0xffffb000, v170
	s_nop 1
	v_addc_co_u32_e32 v171, vcc, -1, v171, vcc
	v_add_f32_e32 v0, v126, v210
	v_add_f32_e32 v163, v168, v214
	v_add_f32_e32 v167, v127, v211
	v_add_f32_e32 v170, v169, v215
	v_add_f32_e32 v171, v128, v212
	v_add_f32_e32 v172, v124, v216
	v_add_f32_e32 v173, v129, v213
	v_add_f32_e32 v174, v125, v217
	v_mul_f32_e32 v0, 0xbfb8aa3b, v0
	v_mul_f32_e32 v163, 0xbfb8aa3b, v163
	v_mul_f32_e32 v167, 0xbfb8aa3b, v167
	v_mul_f32_e32 v170, 0xbfb8aa3b, v170
	v_mul_f32_e32 v171, 0xbfb8aa3b, v171
	v_mul_f32_e32 v172, 0xbfb8aa3b, v172
	v_mul_f32_e32 v173, 0xbfb8aa3b, v173
	v_mul_f32_e32 v174, 0xbfb8aa3b, v174
	v_exp_f32_e32 v0, v0
	v_exp_f32_e32 v163, v163
	v_exp_f32_e32 v167, v167
	v_exp_f32_e32 v170, v170
	v_exp_f32_e32 v171, v171
	v_exp_f32_e32 v172, v172
	v_exp_f32_e32 v173, v173
	v_exp_f32_e32 v174, v174
	v_add_f32_e32 v0, 1.0, v0
	v_add_f32_e32 v163, 1.0, v163
	v_add_f32_e32 v167, 1.0, v167
	v_add_f32_e32 v170, 1.0, v170
	v_add_f32_e32 v171, 1.0, v171
	v_add_f32_e32 v175, 1.0, v172
	v_add_f32_e32 v184, 1.0, v173
	v_add_f32_e32 v185, 1.0, v174
	v_rcp_f32_e32 v176, v0
	v_rcp_f32_e32 v172, v163
	v_rcp_f32_e32 v177, v167
	v_rcp_f32_e32 v173, v170
	v_rcp_f32_e32 v174, v171
	v_rcp_f32_e32 v170, v175
	v_rcp_f32_e32 v175, v184
	v_rcp_f32_e32 v171, v185

;     __device__ __forceinline__ void operator()(const f32x4 (&acc)[2][2][4][2], const Unit& u, int wr, int wc, int fr, int fq) const {
;     ...
;                     else if (type == 5) { const float* bp = bgate + (col0 + bj * HALF - PC_GATE); const f32x4 b0 = *(const f32x4*)bp, b1 = *(const f32x4*)(bp + 4);
; #pragma unroll
;                         for (int e = 0; e < 4; ++e) { v0[e] = __builtin_amdgcn_rcpf(1.f + __builtin_amdgcn_exp2f(-1.4426950408889634f * (v0[e] + b0[e]))); v1[e] = __builtin_amdgcn_rcpf(1.f + __builtin_amdgcn_exp2f(-1.4426950408889634f * (v1[e] + b1[e]))); } }
;                     store8(rowp + bj * HALF, v0, v1);
.LBB0_638:
	v_mov_b32_e32 v126, v166
	v_mov_b32_e32 v127, v166
	v_pk_mul_f32 v[120:121], v[120:121], v[126:127]
	v_pk_mul_f32 v[116:117], v[116:117], v[126:127]
	v_cndmask_b32_e64 v126, 0, 1, s[86:87]
	v_pk_mul_f32 v[118:119], v[118:119], v[166:167]
	v_pk_mul_f32 v[114:115], v[114:115], v[166:167]
	s_andn2_b64 vcc, exec, s[10:11]
	v_cmp_ne_u32_e64 s[10:11], 1, v126
	s_cbranch_vccnz .LBB0_646
	s_and_b64 vcc, exec, s[10:11]
	s_cbranch_vccnz .LBB0_643
	s_andn2_b64 vcc, exec, s[84:85]
	v_mov_b32_e32 v127, v117
	v_mov_b32_e32 v126, v116
	v_mov_b32_e32 v129, v115
	v_mov_b32_e32 v128, v114
	v_mov_b32_e32 v167, v121
	v_mov_b32_e32 v166, v120
	v_mov_b32_e32 v169, v119
	v_mov_b32_e32 v168, v118
	s_cbranch_vccnz .LBB0_642
	s_movk_i32 s0, 0xb200
	v_lshl_add_u64 v[126:127], v[122:123], 2, v[146:147]
	s_mov_b32 s1, -1
	v_lshl_add_u64 v[166:167], v[126:127], 0, s[0:1]
	v_add_co_u32_e32 v126, vcc, 0xffffc000, v126
	s_nop 1
	v_addc_co_u32_e32 v127, vcc, -1, v127, vcc
	v_add_f32_e32 v126, v118, v218
	v_add_f32_e32 v166, v114, v222
	v_add_f32_e32 v127, v119, v219
	v_add_f32_e32 v167, v115, v223
	v_add_f32_e32 v128, v120, v220
	v_add_f32_e32 v168, v116, v224
	v_add_f32_e32 v129, v121, v221
	v_add_f32_e32 v169, v117, v225
	v_mul_f32_e32 v126, 0xbfb8aa3b, v126
	v_mul_f32_e32 v166, 0xbfb8aa3b, v166
	v_mul_f32_e32 v127, 0xbfb8aa3b, v127
	v_mul_f32_e32 v167, 0xbfb8aa3b, v167
	v_mul_f32_e32 v128, 0xbfb8aa3b, v128
	v_mul_f32_e32 v168, 0xbfb8aa3b, v168
	v_mul_f32_e32 v129, 0xbfb8aa3b, v129
	v_mul_f32_e32 v169, 0xbfb8aa3b, v169
	v_exp_f32_e32 v126, v126
	v_exp_f32_e32 v166, v166
	v_exp_f32_e32 v127, v127
	v_exp_f32_e32 v167, v167
	v_exp_f32_e32 v128, v128
	v_exp_f32_e32 v168, v168
	v_exp_f32_e32 v129, v129
	v_exp_f32_e32 v169, v169
	v_add_f32_e32 v126, 1.0, v126
	v_add_f32_e32 v166, 1.0, v166
	v_add_f32_e32 v127, 1.0, v127
	v_add_f32_e32 v167, 1.0, v167
	v_add_f32_e32 v170, 1.0, v128
	v_add_f32_e32 v171, 1.0, v168
	v_add_f32_e32 v172, 1.0, v129
	v_add_f32_e32 v173, 1.0, v169
	v_rcp_f32_e32 v168, v126
	v_rcp_f32_e32 v128, v166
	v_rcp_f32_e32 v169, v127
	v_rcp_f32_e32 v129, v167
	v_rcp_f32_e32 v166, v170
	v_rcp_f32_e32 v126, v171
	v_rcp_f32_e32 v167, v172
	v_rcp_f32_e32 v127, v173

;     __device__ __forceinline__ void operator()(const f32x4 (&acc)[2][2][4][2], const Unit& u, int wr, int wc, int fr, int fq) const {
;     ...
;                 const int row = row0 + ai * HALF + m * 16, pos = row & (SEQ - 1);
;                 bf16_t* rowp = P + (size_t)row * NIN + col0;
;                 const float rstd = rsqrtf(ssq_x[row] * (1.f / DM) + EPS);
.LBB0_652:
	v_or_b32_e32 v124, 16, v160
	v_ashrrev_i32_e32 v125, 31, v124
	s_waitcnt lgkmcnt(0)
	v_lshl_add_u64 v[114:115], v[124:125], 2, s[40:41]
	s_cmp_lt_i32 s45, 4
	s_cbranch_scc1 .LBB0_657
	s_cmp_eq_u32 s45, 4
	s_cselect_b64 s[14:15], -1, 0
	s_cbranch_execz .LBB0_658
	v_mov_b64_e32 v[118:119], v[150:151]
	v_mov_b64_e32 v[114:115], v[148:149]
	s_mov_b32 s0, s45
	s_and_b64 vcc, exec, s[14:15]
	s_cbranch_vccnz .LBB0_661
.LBB0_655:
	v_mov_b32_e32 v114, 1.0
	v_mov_b32_e32 v118, 0
	v_mov_b32_e32 v119, v118
	v_mov_b32_e32 v120, v118
	v_mov_b32_e32 v121, v118
	v_mov_b32_e32 v115, v114
	v_mov_b32_e32 v116, v114
	v_mov_b32_e32 v117, v114
	v_fmamk_f32 v0, v203, 0x3a800000, v235
	s_cmp_lt_i32 s45, 4
	v_cmp_gt_f32_e64 s[14:15], s58, v0
	s_cbranch_scc0 .LBB0_662

;     __device__ __forceinline__ void operator()(const f32x4 (&acc)[2][2][4][2], const Unit& u, int wr, int wc, int fr, int fq) const {
;     ...
;                 const int row = row0 + ai * HALF + m * 16, pos = row & (SEQ - 1);
;                 bf16_t* rowp = P + (size_t)row * NIN + col0;
;                 const float rstd = rsqrtf(ssq_x[row] * (1.f / DM) + EPS);
;                 float ss = 0.f;
;                 f32x4 c4 = (f32x4){1.f, 1.f, 1.f, 1.f}, s4 = (f32x4){0.f, 0.f, 0.f, 0.f};
;                 if (type == 0) { const int a = 4 * (wc & 1) + fq; c4 = *(const f32x4*)(cos64 + pos * 32 + 4 * a); s4 = *(const f32x4*)(sin64 + pos * 32 + 4 * a); }
.LBB0_661:
	v_and_b32_e32 v0, 0x1fdf, v124
	v_lshlrev_b32_e32 v0, s0, v0
	v_lshlrev_b64 v[120:121], 2, v[0:1]
	v_lshl_add_u64 v[114:115], v[114:115], 0, v[120:121]
	v_lshl_add_u64 v[118:119], v[118:119], 0, v[120:121]
	global_load_dwordx4 v[114:117], v[114:115], off
	s_nop 0
	global_load_dwordx4 v[118:121], v[118:119], off
	v_fmamk_f32 v0, v203, 0x3a800000, v235
	s_cmp_lt_i32 s45, 4
	v_cmp_gt_f32_e64 s[14:15], s58, v0
	s_cbranch_scc1 .LBB0_656

;     __device__ __forceinline__ void operator()(const f32x4 (&acc)[2][2][4][2], const Unit& u, int wr, int wc, int fr, int fq) const {
;     ...
;                 const float rstd = rsqrtf(ssq_x[row] * (1.f / DM) + EPS);
;                 float ss = 0.f;
;                 f32x4 c4 = (f32x4){1.f, 1.f, 1.f, 1.f}, s4 = (f32x4){0.f, 0.f, 0.f, 0.f};
;                 if (type == 0) { const int a = 4 * (wc & 1) + fq; c4 = *(const f32x4*)(cos64 + pos * 32 + 4 * a); s4 = *(const f32x4*)(sin64 + pos * 32 + 4 * a); }
;                 else if (type == 4) { c4 = *(const f32x4*)(cos32 + pos * 16 + 4 * fq); s4 = *(const f32x4*)(sin32 + pos * 16 + 4 * fq); }
; #pragma unroll
;                 for (int bj = 0; bj < 2; ++bj) {
;                     f32x4 v0 = acc[ai][bj][m][0] * rstd, v1 = acc[ai][bj][m][1] * rstd;
;                     if (type == 0 || type == 4) { const f32x4 lo = v0 * c4 - v1 * s4, hi_ = v1 * c4 + v0 * s4; v0 = lo * qs; v1 = hi_ * qs; }
;                     else if (type == 2 || type == 3) { ss += (v0[0] * v0[0] + v0[1] * v0[1]) + (v0[2] * v0[2] + v0[3] * v0[3]) + (v1[0] * v1[0] + v1[1] * v1[1]) + (v1[2] * v1[2] + v1[3] * v1[3]); }
;                     else if (type == 5) { const float* bp = bgate + (col0 + bj * HALF - PC_GATE); const f32x4 b0 = *(const f32x4*)bp, b1 = *(const f32x4*)(bp + 4);
; #pragma unroll
;                         for (int e = 0; e < 4; ++e) { v0[e] = __builtin_amdgcn_rcpf(1.f + __builtin_amdgcn_exp2f(-1.4426950408889634f * (v0[e] + b0[e]))); v1[e] = __builtin_amdgcn_rcpf(1.f + __builtin_amdgcn_exp2f(-1.4426950408889634f * (v1[e] + b1[e]))); } }
.LBB0_664:
	v_mul_f32_e32 v126, 0x4b800000, v0
	v_cndmask_b32_e64 v0, v0, v126, s[14:15]
	v_rsq_f32_e32 v0, v0
	s_andn2_b64 vcc, exec, s[62:63]
	v_mul_f32_e32 v126, 0x45800000, v0
	v_cndmask_b32_e64 v126, v0, v126, s[14:15]
	v_pk_mul_f32 v[112:113], v[112:113], v[126:127] op_sel_hi:[1,0]
	v_pk_mul_f32 v[110:111], v[110:111], v[126:127] op_sel_hi:[1,0]
	v_pk_mul_f32 v[108:109], v[108:109], v[126:127] op_sel_hi:[1,0]
	v_pk_mul_f32 v[106:107], v[106:107], v[126:127] op_sel_hi:[1,0]
	s_cbranch_vccnz .LBB0_672
	s_and_b64 vcc, exec, s[10:11]
	s_cbranch_vccnz .LBB0_669
	s_andn2_b64 vcc, exec, s[84:85]
	v_mov_b32_e32 v129, v109
	v_mov_b32_e32 v128, v108
	v_mov_b32_e32 v131, v107
	v_mov_b32_e32 v130, v106
	v_mov_b32_e32 v133, v113
	v_mov_b32_e32 v132, v112
	v_mov_b32_e32 v135, v111
	v_mov_b32_e32 v134, v110
	s_cbranch_vccnz .LBB0_668
	s_movk_i32 s0, 0xb000
	v_lshl_add_u64 v[128:129], v[122:123], 2, v[146:147]
	s_mov_b32 s1, -1
	v_lshl_add_u64 v[132:133], v[128:129], 0, s[0:1]
	v_add_co_u32_e32 v128, vcc, 0xffffb000, v128
	s_nop 1
	v_addc_co_u32_e32 v129, vcc, -1, v129, vcc
	v_add_f32_e32 v0, v110, v210
	v_add_f32_e32 v127, v106, v214
	v_add_f32_e32 v128, v111, v211
	v_add_f32_e32 v129, v107, v215
	v_add_f32_e32 v130, v112, v212
	v_add_f32_e32 v132, v108, v216
	v_add_f32_e32 v131, v113, v213
	v_add_f32_e32 v133, v109, v217
	v_mul_f32_e32 v0, 0xbfb8aa3b, v0
	v_mul_f32_e32 v127, 0xbfb8aa3b, v127
	v_mul_f32_e32 v128, 0xbfb8aa3b, v128
	v_mul_f32_e32 v129, 0xbfb8aa3b, v129
	v_mul_f32_e32 v130, 0xbfb8aa3b, v130
	v_mul_f32_e32 v132, 0xbfb8aa3b, v132
	v_mul_f32_e32 v131, 0xbfb8aa3b, v131
	v_mul_f32_e32 v133, 0xbfb8aa3b, v133
	v_exp_f32_e32 v0, v0
	v_exp_f32_e32 v127, v127
	v_exp_f32_e32 v128, v128
	v_exp_f32_e32 v129, v129
	v_exp_f32_e32 v130, v130
	v_exp_f32_e32 v132, v132
	v_exp_f32_e32 v131, v131
	v_exp_f32_e32 v133, v133
	v_add_f32_e32 v0, 1.0, v0
	v_add_f32_e32 v127, 1.0, v127
	v_add_f32_e32 v128, 1.0, v128
	v_add_f32_e32 v129, 1.0, v129
	v_add_f32_e32 v136, 1.0, v130
	v_add_f32_e32 v137, 1.0, v132
	v_add_f32_e32 v166, 1.0, v131
	v_add_f32_e32 v167, 1.0, v133
	v_rcp_f32_e32 v134, v0
	v_rcp_f32_e32 v130, v127
	v_rcp_f32_e32 v135, v128
	v_rcp_f32_e32 v131, v129
	v_rcp_f32_e32 v132, v136
	v_rcp_f32_e32 v128, v137
	v_rcp_f32_e32 v133, v166
	v_rcp_f32_e32 v129, v167

;     __device__ __forceinline__ void operator()(const f32x4 (&acc)[2][2][4][2], const Unit& u, int wr, int wc, int fr, int fq) const {
;     ...
;                     else if (type == 5) { const float* bp = bgate + (col0 + bj * HALF - PC_GATE); const f32x4 b0 = *(const f32x4*)bp, b1 = *(const f32x4*)(bp + 4);
; #pragma unroll
;                         for (int e = 0; e < 4; ++e) { v0[e] = __builtin_amdgcn_rcpf(1.f + __builtin_amdgcn_exp2f(-1.4426950408889634f * (v0[e] + b0[e]))); v1[e] = __builtin_amdgcn_rcpf(1.f + __builtin_amdgcn_exp2f(-1.4426950408889634f * (v1[e] + b1[e]))); } }
;                     store8(rowp + bj * HALF, v0, v1);
.LBB0_678:
	v_mov_b32_e32 v108, v126
	v_mov_b32_e32 v109, v126
	v_pk_mul_f32 v[104:105], v[104:105], v[108:109]
	v_pk_mul_f32 v[102:103], v[102:103], v[126:127]
	v_pk_mul_f32 v[100:101], v[100:101], v[108:109]
	s_andn2_b64 vcc, exec, s[60:61]
	v_pk_mul_f32 v[98:99], v[98:99], v[126:127]
	s_cbranch_vccnz .LBB0_686
	s_and_b64 vcc, exec, s[10:11]
	s_cbranch_vccnz .LBB0_683
	s_andn2_b64 vcc, exec, s[84:85]
	v_mov_b32_e32 v109, v101
	v_mov_b32_e32 v108, v100
	v_mov_b32_e32 v111, v99
	v_mov_b32_e32 v110, v98
	v_mov_b32_e32 v113, v105
	v_mov_b32_e32 v112, v104
	v_mov_b32_e32 v125, v103
	v_mov_b32_e32 v124, v102
	s_cbranch_vccnz .LBB0_682
	s_movk_i32 s0, 0xb200
	v_lshl_add_u64 v[108:109], v[122:123], 2, v[146:147]
	s_mov_b32 s1, -1
	v_lshl_add_u64 v[112:113], v[108:109], 0, s[0:1]
	v_add_co_u32_e32 v108, vcc, 0xffffc000, v108
	s_nop 1
	v_addc_co_u32_e32 v109, vcc, -1, v109, vcc
	v_add_f32_e32 v108, v102, v218
	v_add_f32_e32 v112, v98, v222
	v_add_f32_e32 v109, v103, v219
	v_add_f32_e32 v113, v99, v223
	v_add_f32_e32 v110, v104, v220
	v_add_f32_e32 v124, v100, v224
	v_add_f32_e32 v111, v105, v221
	v_add_f32_e32 v125, v101, v225
	v_mul_f32_e32 v108, 0xbfb8aa3b, v108
	v_mul_f32_e32 v112, 0xbfb8aa3b, v112
	v_mul_f32_e32 v109, 0xbfb8aa3b, v109
	v_mul_f32_e32 v113, 0xbfb8aa3b, v113
	v_mul_f32_e32 v110, 0xbfb8aa3b, v110
	v_mul_f32_e32 v124, 0xbfb8aa3b, v124
	v_mul_f32_e32 v111, 0xbfb8aa3b, v111
	v_mul_f32_e32 v125, 0xbfb8aa3b, v125
	v_exp_f32_e32 v108, v108
	v_exp_f32_e32 v112, v112
	v_exp_f32_e32 v109, v109
	v_exp_f32_e32 v113, v113
	v_exp_f32_e32 v110, v110
	v_exp_f32_e32 v124, v124
	v_exp_f32_e32 v111, v111
	v_exp_f32_e32 v125, v125
	v_add_f32_e32 v108, 1.0, v108
	v_add_f32_e32 v112, 1.0, v112
	v_add_f32_e32 v109, 1.0, v109
	v_add_f32_e32 v113, 1.0, v113
	v_add_f32_e32 v126, 1.0, v110
	v_add_f32_e32 v127, 1.0, v124
	v_add_f32_e32 v128, 1.0, v111
	v_add_f32_e32 v129, 1.0, v125
	v_rcp_f32_e32 v124, v108
	v_rcp_f32_e32 v110, v112
	v_rcp_f32_e32 v125, v109
	v_rcp_f32_e32 v111, v113
	v_rcp_f32_e32 v112, v126
	v_rcp_f32_e32 v108, v127
	v_rcp_f32_e32 v113, v128
	v_rcp_f32_e32 v109, v129

;     __device__ __forceinline__ void operator()(const f32x4 (&acc)[2][2][4][2], const Unit& u, int wr, int wc, int fr, int fq) const {
;     ...
;                 const int row = row0 + ai * HALF + m * 16, pos = row & (SEQ - 1);
;                 bf16_t* rowp = P + (size_t)row * NIN + col0;
;                 const float rstd = rsqrtf(ssq_x[row] * (1.f / DM) + EPS);
.LBB0_692:
	v_or_b32_e32 v106, 32, v160
	v_ashrrev_i32_e32 v107, 31, v106
	s_waitcnt lgkmcnt(0)
	v_lshl_add_u64 v[98:99], v[106:107], 2, s[40:41]
	s_cmp_lt_i32 s45, 4
	s_cbranch_scc1 .LBB0_697
	s_cmp_eq_u32 s45, 4
	s_cselect_b64 s[14:15], -1, 0
	s_cbranch_execz .LBB0_698
	v_mov_b64_e32 v[102:103], v[150:151]
	v_mov_b64_e32 v[98:99], v[148:149]
	s_mov_b32 s0, s45
	s_and_b64 vcc, exec, s[14:15]
	s_cbranch_vccnz .LBB0_701
.LBB0_695:
	v_mov_b32_e32 v98, 1.0
	v_mov_b32_e32 v102, 0
	v_mov_b32_e32 v103, v102
	v_mov_b32_e32 v104, v102
	v_mov_b32_e32 v105, v102
	v_mov_b32_e32 v99, v98
	v_mov_b32_e32 v100, v98
	v_mov_b32_e32 v101, v98
	v_fmamk_f32 v0, v204, 0x3a800000, v235
	s_cmp_lt_i32 s45, 4
	v_cmp_gt_f32_e64 s[14:15], s58, v0
	s_cbranch_scc0 .LBB0_702

;     __device__ __forceinline__ void operator()(const f32x4 (&acc)[2][2][4][2], const Unit& u, int wr, int wc, int fr, int fq) const {
;     ...
;                 const int row = row0 + ai * HALF + m * 16, pos = row & (SEQ - 1);
;                 bf16_t* rowp = P + (size_t)row * NIN + col0;
;                 const float rstd = rsqrtf(ssq_x[row] * (1.f / DM) + EPS);
;                 float ss = 0.f;
;                 f32x4 c4 = (f32x4){1.f, 1.f, 1.f, 1.f}, s4 = (f32x4){0.f, 0.f, 0.f, 0.f};
;                 if (type == 0) { const int a = 4 * (wc & 1) + fq; c4 = *(const f32x4*)(cos64 + pos * 32 + 4 * a); s4 = *(const f32x4*)(sin64 + pos * 32 + 4 * a); }
.LBB0_701:
	v_and_b32_e32 v0, 0x1fef, v106
	v_lshlrev_b32_e32 v0, s0, v0
	v_lshlrev_b64 v[104:105], 2, v[0:1]
	v_lshl_add_u64 v[98:99], v[98:99], 0, v[104:105]
	v_lshl_add_u64 v[102:103], v[102:103], 0, v[104:105]
	global_load_dwordx4 v[98:101], v[98:99], off
	s_nop 0
	global_load_dwordx4 v[102:105], v[102:103], off
	v_fmamk_f32 v0, v204, 0x3a800000, v235
	s_cmp_lt_i32 s45, 4
	v_cmp_gt_f32_e64 s[14:15], s58, v0
	s_cbranch_scc1 .LBB0_696

;     __device__ __forceinline__ void operator()(const f32x4 (&acc)[2][2][4][2], const Unit& u, int wr, int wc, int fr, int fq) const {
;     ...
;                 const float rstd = rsqrtf(ssq_x[row] * (1.f / DM) + EPS);
;                 float ss = 0.f;
;                 f32x4 c4 = (f32x4){1.f, 1.f, 1.f, 1.f}, s4 = (f32x4){0.f, 0.f, 0.f, 0.f};
;                 if (type == 0) { const int a = 4 * (wc & 1) + fq; c4 = *(const f32x4*)(cos64 + pos * 32 + 4 * a); s4 = *(const f32x4*)(sin64 + pos * 32 + 4 * a); }
;                 else if (type == 4) { c4 = *(const f32x4*)(cos32 + pos * 16 + 4 * fq); s4 = *(const f32x4*)(sin32 + pos * 16 + 4 * fq); }
; #pragma unroll
;                 for (int bj = 0; bj < 2; ++bj) {
;                     f32x4 v0 = acc[ai][bj][m][0] * rstd, v1 = acc[ai][bj][m][1] * rstd;
;                     if (type == 0 || type == 4) { const f32x4 lo = v0 * c4 - v1 * s4, hi_ = v1 * c4 + v0 * s4; v0 = lo * qs; v1 = hi_ * qs; }
;                     else if (type == 2 || type == 3) { ss += (v0[0] * v0[0] + v0[1] * v0[1]) + (v0[2] * v0[2] + v0[3] * v0[3]) + (v1[0] * v1[0] + v1[1] * v1[1]) + (v1[2] * v1[2] + v1[3] * v1[3]); }
;                     else if (type == 5) { const float* bp = bgate + (col0 + bj * HALF - PC_GATE); const f32x4 b0 = *(const f32x4*)bp, b1 = *(const f32x4*)(bp + 4);
; #pragma unroll
;                         for (int e = 0; e < 4; ++e) { v0[e] = __builtin_amdgcn_rcpf(1.f + __builtin_amdgcn_exp2f(-1.4426950408889634f * (v0[e] + b0[e]))); v1[e] = __builtin_amdgcn_rcpf(1.f + __builtin_amdgcn_exp2f(-1.4426950408889634f * (v1[e] + b1[e]))); } }
.LBB0_704:
	v_mul_f32_e32 v108, 0x4b800000, v0
	v_cndmask_b32_e64 v0, v0, v108, s[14:15]
	v_rsq_f32_e32 v0, v0
	s_andn2_b64 vcc, exec, s[62:63]
	v_mul_f32_e32 v108, 0x45800000, v0
	v_cndmask_b32_e64 v108, v0, v108, s[14:15]
	v_pk_mul_f32 v[96:97], v[96:97], v[108:109] op_sel_hi:[1,0]
	v_pk_mul_f32 v[94:95], v[94:95], v[108:109] op_sel_hi:[1,0]
	v_pk_mul_f32 v[92:93], v[92:93], v[108:109] op_sel_hi:[1,0]
	v_pk_mul_f32 v[90:91], v[90:91], v[108:109] op_sel_hi:[1,0]
	s_cbranch_vccnz .LBB0_712
	s_and_b64 vcc, exec, s[10:11]
	s_cbranch_vccnz .LBB0_709
	s_andn2_b64 vcc, exec, s[84:85]
	v_mov_b32_e32 v111, v93
	v_mov_b32_e32 v110, v92
	v_mov_b32_e32 v113, v91
	v_mov_b32_e32 v112, v90
	v_mov_b32_e32 v115, v97
	v_mov_b32_e32 v114, v96
	v_mov_b32_e32 v117, v95
	v_mov_b32_e32 v116, v94
	s_cbranch_vccnz .LBB0_708
	s_movk_i32 s0, 0xb000
	v_lshl_add_u64 v[110:111], v[122:123], 2, v[146:147]
	s_mov_b32 s1, -1
	v_lshl_add_u64 v[114:115], v[110:111], 0, s[0:1]
	v_add_co_u32_e32 v110, vcc, 0xffffb000, v110
	s_nop 1
	v_addc_co_u32_e32 v111, vcc, -1, v111, vcc
	v_add_f32_e32 v0, v94, v210
	v_add_f32_e32 v109, v90, v214
	v_add_f32_e32 v110, v95, v211
	v_add_f32_e32 v111, v91, v215
	v_add_f32_e32 v112, v96, v212
	v_add_f32_e32 v114, v92, v216
	v_add_f32_e32 v113, v97, v213
	v_add_f32_e32 v115, v93, v217
	v_mul_f32_e32 v0, 0xbfb8aa3b, v0
	v_mul_f32_e32 v109, 0xbfb8aa3b, v109
	v_mul_f32_e32 v110, 0xbfb8aa3b, v110
	v_mul_f32_e32 v111, 0xbfb8aa3b, v111
	v_mul_f32_e32 v112, 0xbfb8aa3b, v112
	v_mul_f32_e32 v114, 0xbfb8aa3b, v114
	v_mul_f32_e32 v113, 0xbfb8aa3b, v113
	v_mul_f32_e32 v115, 0xbfb8aa3b, v115
	v_exp_f32_e32 v0, v0
	v_exp_f32_e32 v109, v109
	v_exp_f32_e32 v110, v110
	v_exp_f32_e32 v111, v111
	v_exp_f32_e32 v112, v112
	v_exp_f32_e32 v114, v114
	v_exp_f32_e32 v113, v113
	v_exp_f32_e32 v115, v115
	v_add_f32_e32 v0, 1.0, v0
	v_add_f32_e32 v109, 1.0, v109
	v_add_f32_e32 v110, 1.0, v110
	v_add_f32_e32 v111, 1.0, v111
	v_add_f32_e32 v118, 1.0, v112
	v_add_f32_e32 v119, 1.0, v114
	v_add_f32_e32 v120, 1.0, v113
	v_add_f32_e32 v121, 1.0, v115
	v_rcp_f32_e32 v116, v0
	v_rcp_f32_e32 v112, v109
	v_rcp_f32_e32 v117, v110
	v_rcp_f32_e32 v113, v111
	v_rcp_f32_e32 v114, v118
	v_rcp_f32_e32 v110, v119
	v_rcp_f32_e32 v115, v120
	v_rcp_f32_e32 v111, v121

;     __device__ __forceinline__ void operator()(const f32x4 (&acc)[2][2][4][2], const Unit& u, int wr, int wc, int fr, int fq) const {
;     ...
;                     else if (type == 5) { const float* bp = bgate + (col0 + bj * HALF - PC_GATE); const f32x4 b0 = *(const f32x4*)bp, b1 = *(const f32x4*)(bp + 4);
; #pragma unroll
;                         for (int e = 0; e < 4; ++e) { v0[e] = __builtin_amdgcn_rcpf(1.f + __builtin_amdgcn_exp2f(-1.4426950408889634f * (v0[e] + b0[e]))); v1[e] = __builtin_amdgcn_rcpf(1.f + __builtin_amdgcn_exp2f(-1.4426950408889634f * (v1[e] + b1[e]))); } }
;                     store8(rowp + bj * HALF, v0, v1);
.LBB0_718:
	v_mov_b32_e32 v92, v108
	v_mov_b32_e32 v93, v108
	v_pk_mul_f32 v[88:89], v[88:89], v[92:93]
	v_pk_mul_f32 v[86:87], v[86:87], v[108:109]
	v_pk_mul_f32 v[84:85], v[84:85], v[92:93]
	s_andn2_b64 vcc, exec, s[60:61]
	v_pk_mul_f32 v[82:83], v[82:83], v[108:109]
	s_cbranch_vccnz .LBB0_726
	s_and_b64 vcc, exec, s[10:11]
	s_cbranch_vccnz .LBB0_723
	s_andn2_b64 vcc, exec, s[84:85]
	v_mov_b32_e32 v93, v85
	v_mov_b32_e32 v92, v84
	v_mov_b32_e32 v95, v83
	v_mov_b32_e32 v94, v82
	v_mov_b32_e32 v97, v89
	v_mov_b32_e32 v96, v88
	v_mov_b32_e32 v107, v87
	v_mov_b32_e32 v106, v86
	s_cbranch_vccnz .LBB0_722
	s_movk_i32 s0, 0xb200
	v_lshl_add_u64 v[92:93], v[122:123], 2, v[146:147]
	s_mov_b32 s1, -1
	v_lshl_add_u64 v[96:97], v[92:93], 0, s[0:1]
	v_add_co_u32_e32 v92, vcc, 0xffffc000, v92
	s_nop 1
	v_addc_co_u32_e32 v93, vcc, -1, v93, vcc
	v_add_f32_e32 v92, v86, v218
	v_add_f32_e32 v96, v82, v222
	v_add_f32_e32 v93, v87, v219
	v_add_f32_e32 v97, v83, v223
	v_add_f32_e32 v94, v88, v220
	v_add_f32_e32 v106, v84, v224
	v_add_f32_e32 v95, v89, v221
	v_add_f32_e32 v107, v85, v225
	v_mul_f32_e32 v92, 0xbfb8aa3b, v92
	v_mul_f32_e32 v96, 0xbfb8aa3b, v96
	v_mul_f32_e32 v93, 0xbfb8aa3b, v93
	v_mul_f32_e32 v97, 0xbfb8aa3b, v97
	v_mul_f32_e32 v94, 0xbfb8aa3b, v94
	v_mul_f32_e32 v106, 0xbfb8aa3b, v106
	v_mul_f32_e32 v95, 0xbfb8aa3b, v95
	v_mul_f32_e32 v107, 0xbfb8aa3b, v107
	v_exp_f32_e32 v92, v92
	v_exp_f32_e32 v96, v96
	v_exp_f32_e32 v93, v93
	v_exp_f32_e32 v97, v97
	v_exp_f32_e32 v94, v94
	v_exp_f32_e32 v106, v106
	v_exp_f32_e32 v95, v95
	v_exp_f32_e32 v107, v107
	v_add_f32_e32 v92, 1.0, v92
	v_add_f32_e32 v96, 1.0, v96
	v_add_f32_e32 v93, 1.0, v93
	v_add_f32_e32 v97, 1.0, v97
	v_add_f32_e32 v108, 1.0, v94
	v_add_f32_e32 v109, 1.0, v106
	v_add_f32_e32 v110, 1.0, v95
	v_add_f32_e32 v111, 1.0, v107
	v_rcp_f32_e32 v106, v92
	v_rcp_f32_e32 v94, v96
	v_rcp_f32_e32 v107, v93
	v_rcp_f32_e32 v95, v97
	v_rcp_f32_e32 v96, v108
	v_rcp_f32_e32 v92, v109
	v_rcp_f32_e32 v97, v110
	v_rcp_f32_e32 v93, v111

;     __device__ __forceinline__ void operator()(const f32x4 (&acc)[2][2][4][2], const Unit& u, int wr, int wc, int fr, int fq) const {
;     ...
;                 const int row = row0 + ai * HALF + m * 16, pos = row & (SEQ - 1);
;                 bf16_t* rowp = P + (size_t)row * NIN + col0;
;                 const float rstd = rsqrtf(ssq_x[row] * (1.f / DM) + EPS);
.LBB0_732:
	v_or_b32_e32 v90, 48, v160
	v_ashrrev_i32_e32 v91, 31, v90
	s_waitcnt lgkmcnt(0)
	v_lshl_add_u64 v[82:83], v[90:91], 2, s[40:41]
	s_cmp_lt_i32 s45, 4
	s_cbranch_scc1 .LBB0_737
	s_cmp_eq_u32 s45, 4
	s_cselect_b64 s[14:15], -1, 0
	s_cbranch_execz .LBB0_738
	v_mov_b64_e32 v[86:87], v[150:151]
	v_mov_b64_e32 v[82:83], v[148:149]
	s_mov_b32 s0, s45
	s_and_b64 vcc, exec, s[14:15]
	s_cbranch_vccnz .LBB0_741
.LBB0_735:
	v_mov_b32_e32 v82, 1.0
	v_mov_b32_e32 v86, 0
	v_mov_b32_e32 v87, v86
	v_mov_b32_e32 v88, v86
	v_mov_b32_e32 v89, v86
	v_mov_b32_e32 v83, v82
	v_mov_b32_e32 v84, v82
	v_mov_b32_e32 v85, v82
	v_fmamk_f32 v0, v205, 0x3a800000, v235
	s_cmp_lt_i32 s45, 4
	v_cmp_gt_f32_e64 s[14:15], s58, v0
	s_cbranch_scc0 .LBB0_742

;     __device__ __forceinline__ void operator()(const f32x4 (&acc)[2][2][4][2], const Unit& u, int wr, int wc, int fr, int fq) const {
;     ...
;                 const int row = row0 + ai * HALF + m * 16, pos = row & (SEQ - 1);
;                 bf16_t* rowp = P + (size_t)row * NIN + col0;
;                 const float rstd = rsqrtf(ssq_x[row] * (1.f / DM) + EPS);
;                 float ss = 0.f;
;                 f32x4 c4 = (f32x4){1.f, 1.f, 1.f, 1.f}, s4 = (f32x4){0.f, 0.f, 0.f, 0.f};
;                 if (type == 0) { const int a = 4 * (wc & 1) + fq; c4 = *(const f32x4*)(cos64 + pos * 32 + 4 * a); s4 = *(const f32x4*)(sin64 + pos * 32 + 4 * a); }
.LBB0_741:
	v_and_b32_e32 v0, 0x1fff, v90
	v_lshlrev_b32_e32 v0, s0, v0
	v_lshlrev_b64 v[88:89], 2, v[0:1]
	v_lshl_add_u64 v[82:83], v[82:83], 0, v[88:89]
	v_lshl_add_u64 v[86:87], v[86:87], 0, v[88:89]
	global_load_dwordx4 v[82:85], v[82:83], off
	s_nop 0
	global_load_dwordx4 v[86:89], v[86:87], off
	v_fmamk_f32 v0, v205, 0x3a800000, v235
	s_cmp_lt_i32 s45, 4
	v_cmp_gt_f32_e64 s[14:15], s58, v0
	s_cbranch_scc1 .LBB0_736

;     __device__ __forceinline__ void operator()(const f32x4 (&acc)[2][2][4][2], const Unit& u, int wr, int wc, int fr, int fq) const {
;     ...
;                 const float rstd = rsqrtf(ssq_x[row] * (1.f / DM) + EPS);
;                 float ss = 0.f;
;                 f32x4 c4 = (f32x4){1.f, 1.f, 1.f, 1.f}, s4 = (f32x4){0.f, 0.f, 0.f, 0.f};
;                 if (type == 0) { const int a = 4 * (wc & 1) + fq; c4 = *(const f32x4*)(cos64 + pos * 32 + 4 * a); s4 = *(const f32x4*)(sin64 + pos * 32 + 4 * a); }
;                 else if (type == 4) { c4 = *(const f32x4*)(cos32 + pos * 16 + 4 * fq); s4 = *(const f32x4*)(sin32 + pos * 16 + 4 * fq); }
; #pragma unroll
;                 for (int bj = 0; bj < 2; ++bj) {
;                     f32x4 v0 = acc[ai][bj][m][0] * rstd, v1 = acc[ai][bj][m][1] * rstd;
;                     if (type == 0 || type == 4) { const f32x4 lo = v0 * c4 - v1 * s4, hi_ = v1 * c4 + v0 * s4; v0 = lo * qs; v1 = hi_ * qs; }
;                     else if (type == 2 || type == 3) { ss += (v0[0] * v0[0] + v0[1] * v0[1]) + (v0[2] * v0[2] + v0[3] * v0[3]) + (v1[0] * v1[0] + v1[1] * v1[1]) + (v1[2] * v1[2] + v1[3] * v1[3]); }
;                     else if (type == 5) { const float* bp = bgate + (col0 + bj * HALF - PC_GATE); const f32x4 b0 = *(const f32x4*)bp, b1 = *(const f32x4*)(bp + 4);
; #pragma unroll
;                         for (int e = 0; e < 4; ++e) { v0[e] = __builtin_amdgcn_rcpf(1.f + __builtin_amdgcn_exp2f(-1.4426950408889634f * (v0[e] + b0[e]))); v1[e] = __builtin_amdgcn_rcpf(1.f + __builtin_amdgcn_exp2f(-1.4426950408889634f * (v1[e] + b1[e]))); } }
.LBB0_744:
	v_mul_f32_e32 v92, 0x4b800000, v0
	v_cndmask_b32_e64 v0, v0, v92, s[14:15]
	v_rsq_f32_e32 v0, v0
	s_andn2_b64 vcc, exec, s[62:63]
	v_mul_f32_e32 v92, 0x45800000, v0
	v_cndmask_b32_e64 v92, v0, v92, s[14:15]
	v_pk_mul_f32 v[80:81], v[80:81], v[92:93] op_sel_hi:[1,0]
	v_pk_mul_f32 v[78:79], v[78:79], v[92:93] op_sel_hi:[1,0]
	v_pk_mul_f32 v[76:77], v[76:77], v[92:93] op_sel_hi:[1,0]
	v_pk_mul_f32 v[74:75], v[74:75], v[92:93] op_sel_hi:[1,0]
	s_cbranch_vccnz .LBB0_752
	s_and_b64 vcc, exec, s[10:11]
	s_cbranch_vccnz .LBB0_749
	s_andn2_b64 vcc, exec, s[84:85]
	v_mov_b32_e32 v95, v77
	v_mov_b32_e32 v94, v76
	v_mov_b32_e32 v97, v75
	v_mov_b32_e32 v96, v74
	v_mov_b32_e32 v99, v81
	v_mov_b32_e32 v98, v80
	v_mov_b32_e32 v101, v79
	v_mov_b32_e32 v100, v78
	s_cbranch_vccnz .LBB0_748
	s_movk_i32 s0, 0xb000
	v_lshl_add_u64 v[94:95], v[122:123], 2, v[146:147]
	s_mov_b32 s1, -1
	v_lshl_add_u64 v[98:99], v[94:95], 0, s[0:1]
	v_add_co_u32_e32 v94, vcc, 0xffffb000, v94
	s_nop 1
	v_addc_co_u32_e32 v95, vcc, -1, v95, vcc
	v_add_f32_e32 v0, v78, v210
	v_add_f32_e32 v93, v74, v214
	v_add_f32_e32 v94, v79, v211
	v_add_f32_e32 v95, v75, v215
	v_add_f32_e32 v96, v80, v212
	v_add_f32_e32 v98, v76, v216
	v_add_f32_e32 v97, v81, v213
	v_add_f32_e32 v99, v77, v217
	v_mul_f32_e32 v0, 0xbfb8aa3b, v0
	v_mul_f32_e32 v93, 0xbfb8aa3b, v93
	v_mul_f32_e32 v94, 0xbfb8aa3b, v94
	v_mul_f32_e32 v95, 0xbfb8aa3b, v95
	v_mul_f32_e32 v96, 0xbfb8aa3b, v96
	v_mul_f32_e32 v98, 0xbfb8aa3b, v98
	v_mul_f32_e32 v97, 0xbfb8aa3b, v97
	v_mul_f32_e32 v99, 0xbfb8aa3b, v99
	v_exp_f32_e32 v0, v0
	v_exp_f32_e32 v93, v93
	v_exp_f32_e32 v94, v94
	v_exp_f32_e32 v95, v95
	v_exp_f32_e32 v96, v96
	v_exp_f32_e32 v98, v98
	v_exp_f32_e32 v97, v97
	v_exp_f32_e32 v99, v99
	v_add_f32_e32 v0, 1.0, v0
	v_add_f32_e32 v93, 1.0, v93
	v_add_f32_e32 v94, 1.0, v94
	v_add_f32_e32 v95, 1.0, v95
	v_add_f32_e32 v102, 1.0, v96
	v_add_f32_e32 v103, 1.0, v98
	v_add_f32_e32 v104, 1.0, v97
	v_add_f32_e32 v105, 1.0, v99
	v_rcp_f32_e32 v100, v0
	v_rcp_f32_e32 v96, v93
	v_rcp_f32_e32 v101, v94
	v_rcp_f32_e32 v97, v95
	v_rcp_f32_e32 v98, v102
	v_rcp_f32_e32 v94, v103
	v_rcp_f32_e32 v99, v104
	v_rcp_f32_e32 v95, v105

;     __device__ __forceinline__ void operator()(const f32x4 (&acc)[2][2][4][2], const Unit& u, int wr, int wc, int fr, int fq) const {
;     ...
;                     else if (type == 5) { const float* bp = bgate + (col0 + bj * HALF - PC_GATE); const f32x4 b0 = *(const f32x4*)bp, b1 = *(const f32x4*)(bp + 4);
; #pragma unroll
;                         for (int e = 0; e < 4; ++e) { v0[e] = __builtin_amdgcn_rcpf(1.f + __builtin_amdgcn_exp2f(-1.4426950408889634f * (v0[e] + b0[e]))); v1[e] = __builtin_amdgcn_rcpf(1.f + __builtin_amdgcn_exp2f(-1.4426950408889634f * (v1[e] + b1[e]))); } }
;                     store8(rowp + bj * HALF, v0, v1);
.LBB0_758:
	v_mov_b32_e32 v76, v92
	v_mov_b32_e32 v77, v92
	v_pk_mul_f32 v[72:73], v[72:73], v[76:77]
	v_pk_mul_f32 v[70:71], v[70:71], v[92:93]
	v_pk_mul_f32 v[68:69], v[68:69], v[76:77]
	s_andn2_b64 vcc, exec, s[60:61]
	v_pk_mul_f32 v[66:67], v[66:67], v[92:93]
	s_cbranch_vccnz .LBB0_766
	s_and_b64 vcc, exec, s[10:11]
	s_cbranch_vccnz .LBB0_763
	s_andn2_b64 vcc, exec, s[84:85]
	v_mov_b32_e32 v77, v69
	v_mov_b32_e32 v76, v68
	v_mov_b32_e32 v79, v67
	v_mov_b32_e32 v78, v66
	v_mov_b32_e32 v81, v73
	v_mov_b32_e32 v80, v72
	v_mov_b32_e32 v91, v71
	v_mov_b32_e32 v90, v70
	s_cbranch_vccnz .LBB0_762
	s_movk_i32 s0, 0xb200
	v_lshl_add_u64 v[76:77], v[122:123], 2, v[146:147]
	s_mov_b32 s1, -1
	v_lshl_add_u64 v[80:81], v[76:77], 0, s[0:1]
	v_add_co_u32_e32 v76, vcc, 0xffffc000, v76
	s_nop 1
	v_addc_co_u32_e32 v77, vcc, -1, v77, vcc
	v_add_f32_e32 v76, v70, v218
	v_add_f32_e32 v80, v66, v222
	v_add_f32_e32 v77, v71, v219
	v_add_f32_e32 v81, v67, v223
	v_add_f32_e32 v78, v72, v220
	v_add_f32_e32 v90, v68, v224
	v_add_f32_e32 v79, v73, v221
	v_add_f32_e32 v91, v69, v225
	v_mul_f32_e32 v76, 0xbfb8aa3b, v76
	v_mul_f32_e32 v80, 0xbfb8aa3b, v80
	v_mul_f32_e32 v77, 0xbfb8aa3b, v77
	v_mul_f32_e32 v81, 0xbfb8aa3b, v81
	v_mul_f32_e32 v78, 0xbfb8aa3b, v78
	v_mul_f32_e32 v90, 0xbfb8aa3b, v90
	v_mul_f32_e32 v79, 0xbfb8aa3b, v79
	v_mul_f32_e32 v91, 0xbfb8aa3b, v91
	v_exp_f32_e32 v76, v76
	v_exp_f32_e32 v80, v80
	v_exp_f32_e32 v77, v77
	v_exp_f32_e32 v81, v81
	v_exp_f32_e32 v78, v78
	v_exp_f32_e32 v90, v90
	v_exp_f32_e32 v79, v79
	v_exp_f32_e32 v91, v91
	v_add_f32_e32 v76, 1.0, v76
	v_add_f32_e32 v80, 1.0, v80
	v_add_f32_e32 v77, 1.0, v77
	v_add_f32_e32 v81, 1.0, v81
	v_add_f32_e32 v92, 1.0, v78
	v_add_f32_e32 v93, 1.0, v90
	v_add_f32_e32 v94, 1.0, v79
	v_add_f32_e32 v95, 1.0, v91
	v_rcp_f32_e32 v90, v76
	v_rcp_f32_e32 v78, v80
	v_rcp_f32_e32 v91, v77
	v_rcp_f32_e32 v79, v81
	v_rcp_f32_e32 v80, v92
	v_rcp_f32_e32 v76, v93
	v_rcp_f32_e32 v81, v94
	v_rcp_f32_e32 v77, v95

;     __device__ __forceinline__ void operator()(const f32x4 (&acc)[2][2][4][2], const Unit& u, int wr, int wc, int fr, int fq) const {
;     ...
;                 const int row = row0 + ai * HALF + m * 16, pos = row & (SEQ - 1);
;                 bf16_t* rowp = P + (size_t)row * NIN + col0;
;                 const float rstd = rsqrtf(ssq_x[row] * (1.f / DM) + EPS);
.LBB0_772:
	s_cmp_lt_i32 s45, 4
	s_cbranch_scc1 .LBB0_777
	s_cmp_eq_u32 s45, 4
	s_cselect_b64 s[14:15], -1, 0
	s_cbranch_execz .LBB0_778
	v_mov_b64_e32 v[70:71], v[150:151]
	s_waitcnt lgkmcnt(0)
	v_mov_b64_e32 v[66:67], v[148:149]
	s_mov_b32 s0, s45
	v_add_u32_e32 v74, 0x80, v160
	s_and_b64 vcc, exec, s[14:15]
	s_cbranch_vccnz .LBB0_781
.LBB0_775:
	v_mov_b32_e32 v66, 1.0
	v_mov_b32_e32 v70, 0
	v_mov_b32_e32 v71, v70
	v_mov_b32_e32 v72, v70
	v_mov_b32_e32 v73, v70
	v_mov_b32_e32 v67, v66
	v_mov_b32_e32 v68, v66
	v_mov_b32_e32 v69, v66
	v_fmamk_f32 v0, v206, 0x3a800000, v235
	s_cmp_lt_i32 s45, 4
	v_cmp_gt_f32_e64 s[14:15], s58, v0
	s_cbranch_scc0 .LBB0_782

;     __device__ __forceinline__ void operator()(const f32x4 (&acc)[2][2][4][2], const Unit& u, int wr, int wc, int fr, int fq) const {
;     ...
;                 const int row = row0 + ai * HALF + m * 16, pos = row & (SEQ - 1);
;                 bf16_t* rowp = P + (size_t)row * NIN + col0;
;                 const float rstd = rsqrtf(ssq_x[row] * (1.f / DM) + EPS);
;                 float ss = 0.f;
;                 f32x4 c4 = (f32x4){1.f, 1.f, 1.f, 1.f}, s4 = (f32x4){0.f, 0.f, 0.f, 0.f};
;                 if (type == 0) { const int a = 4 * (wc & 1) + fq; c4 = *(const f32x4*)(cos64 + pos * 32 + 4 * a); s4 = *(const f32x4*)(sin64 + pos * 32 + 4 * a); }
.LBB0_781:
	v_and_b32_e32 v0, 0x1fcf, v74
	v_lshlrev_b32_e32 v0, s0, v0
	v_lshlrev_b64 v[72:73], 2, v[0:1]
	v_lshl_add_u64 v[66:67], v[66:67], 0, v[72:73]
	v_lshl_add_u64 v[70:71], v[70:71], 0, v[72:73]
	global_load_dwordx4 v[66:69], v[66:67], off
	s_nop 0
	global_load_dwordx4 v[70:73], v[70:71], off
	v_fmamk_f32 v0, v206, 0x3a800000, v235
	s_cmp_lt_i32 s45, 4
	v_cmp_gt_f32_e64 s[14:15], s58, v0
	s_cbranch_scc1 .LBB0_776

;     __device__ __forceinline__ void operator()(const f32x4 (&acc)[2][2][4][2], const Unit& u, int wr, int wc, int fr, int fq) const {
;     ...
;                 const float rstd = rsqrtf(ssq_x[row] * (1.f / DM) + EPS);
;                 float ss = 0.f;
;                 f32x4 c4 = (f32x4){1.f, 1.f, 1.f, 1.f}, s4 = (f32x4){0.f, 0.f, 0.f, 0.f};
;                 if (type == 0) { const int a = 4 * (wc & 1) + fq; c4 = *(const f32x4*)(cos64 + pos * 32 + 4 * a); s4 = *(const f32x4*)(sin64 + pos * 32 + 4 * a); }
;                 else if (type == 4) { c4 = *(const f32x4*)(cos32 + pos * 16 + 4 * fq); s4 = *(const f32x4*)(sin32 + pos * 16 + 4 * fq); }
; #pragma unroll
;                 for (int bj = 0; bj < 2; ++bj) {
;                     f32x4 v0 = acc[ai][bj][m][0] * rstd, v1 = acc[ai][bj][m][1] * rstd;
;                     if (type == 0 || type == 4) { const f32x4 lo = v0 * c4 - v1 * s4, hi_ = v1 * c4 + v0 * s4; v0 = lo * qs; v1 = hi_ * qs; }
;                     else if (type == 2 || type == 3) { ss += (v0[0] * v0[0] + v0[1] * v0[1]) + (v0[2] * v0[2] + v0[3] * v0[3]) + (v1[0] * v1[0] + v1[1] * v1[1]) + (v1[2] * v1[2] + v1[3] * v1[3]); }
;                     else if (type == 5) { const float* bp = bgate + (col0 + bj * HALF - PC_GATE); const f32x4 b0 = *(const f32x4*)bp, b1 = *(const f32x4*)(bp + 4);
; #pragma unroll
;                         for (int e = 0; e < 4; ++e) { v0[e] = __builtin_amdgcn_rcpf(1.f + __builtin_amdgcn_exp2f(-1.4426950408889634f * (v0[e] + b0[e]))); v1[e] = __builtin_amdgcn_rcpf(1.f + __builtin_amdgcn_exp2f(-1.4426950408889634f * (v1[e] + b1[e]))); } }
.LBB0_784:
	v_mul_f32_e32 v75, 0x4b800000, v0
	v_cndmask_b32_e64 v0, v0, v75, s[14:15]
	v_rsq_f32_e32 v0, v0
	s_andn2_b64 vcc, exec, s[62:63]
	v_mul_f32_e32 v75, 0x45800000, v0
	v_cndmask_b32_e64 v76, v0, v75, s[14:15]
	v_pk_mul_f32 v[64:65], v[64:65], v[76:77] op_sel_hi:[1,0]
	v_pk_mul_f32 v[62:63], v[62:63], v[76:77] op_sel_hi:[1,0]
	v_pk_mul_f32 v[60:61], v[60:61], v[76:77] op_sel_hi:[1,0]
	v_pk_mul_f32 v[58:59], v[58:59], v[76:77] op_sel_hi:[1,0]
	s_cbranch_vccnz .LBB0_792
	s_and_b64 vcc, exec, s[10:11]
	s_cbranch_vccnz .LBB0_789
	s_andn2_b64 vcc, exec, s[84:85]
	v_mov_b32_e32 v79, v61
	v_mov_b32_e32 v78, v60
	v_mov_b32_e32 v81, v59
	v_mov_b32_e32 v80, v58
	v_mov_b32_e32 v83, v65
	v_mov_b32_e32 v82, v64
	v_mov_b32_e32 v85, v63
	v_mov_b32_e32 v84, v62
	s_cbranch_vccnz .LBB0_788
	s_movk_i32 s0, 0xb000
	v_lshl_add_u64 v[78:79], v[122:123], 2, v[146:147]
	s_mov_b32 s1, -1
	v_lshl_add_u64 v[82:83], v[78:79], 0, s[0:1]
	v_add_co_u32_e32 v78, vcc, 0xffffb000, v78
	s_nop 1
	v_addc_co_u32_e32 v79, vcc, -1, v79, vcc
	v_add_f32_e32 v0, v62, v210
	v_add_f32_e32 v75, v58, v214
	v_add_f32_e32 v77, v63, v211
	v_add_f32_e32 v78, v59, v215
	v_add_f32_e32 v79, v64, v212
	v_add_f32_e32 v80, v60, v216
	v_add_f32_e32 v81, v65, v213
	v_add_f32_e32 v82, v61, v217
	v_mul_f32_e32 v0, 0xbfb8aa3b, v0
	v_mul_f32_e32 v75, 0xbfb8aa3b, v75
	v_mul_f32_e32 v77, 0xbfb8aa3b, v77
	v_mul_f32_e32 v78, 0xbfb8aa3b, v78
	v_mul_f32_e32 v79, 0xbfb8aa3b, v79
	v_mul_f32_e32 v80, 0xbfb8aa3b, v80
	v_mul_f32_e32 v81, 0xbfb8aa3b, v81
	v_mul_f32_e32 v82, 0xbfb8aa3b, v82
	v_exp_f32_e32 v0, v0
	v_exp_f32_e32 v75, v75
	v_exp_f32_e32 v77, v77
	v_exp_f32_e32 v78, v78
	v_exp_f32_e32 v79, v79
	v_exp_f32_e32 v80, v80
	v_exp_f32_e32 v81, v81
	v_exp_f32_e32 v82, v82
	v_add_f32_e32 v0, 1.0, v0
	v_add_f32_e32 v75, 1.0, v75
	v_add_f32_e32 v77, 1.0, v77
	v_add_f32_e32 v78, 1.0, v78
	v_add_f32_e32 v79, 1.0, v79
	v_add_f32_e32 v83, 1.0, v80
	v_add_f32_e32 v86, 1.0, v81
	v_add_f32_e32 v87, 1.0, v82
	v_rcp_f32_e32 v84, v0
	v_rcp_f32_e32 v80, v75
	v_rcp_f32_e32 v85, v77
	v_rcp_f32_e32 v81, v78
	v_rcp_f32_e32 v82, v79
	v_rcp_f32_e32 v78, v83
	v_rcp_f32_e32 v83, v86
	v_rcp_f32_e32 v79, v87

;     __device__ __forceinline__ void operator()(const f32x4 (&acc)[2][2][4][2], const Unit& u, int wr, int wc, int fr, int fq) const {
;     ...
;                     else if (type == 5) { const float* bp = bgate + (col0 + bj * HALF - PC_GATE); const f32x4 b0 = *(const f32x4*)bp, b1 = *(const f32x4*)(bp + 4);
; #pragma unroll
;                         for (int e = 0; e < 4; ++e) { v0[e] = __builtin_amdgcn_rcpf(1.f + __builtin_amdgcn_exp2f(-1.4426950408889634f * (v0[e] + b0[e]))); v1[e] = __builtin_amdgcn_rcpf(1.f + __builtin_amdgcn_exp2f(-1.4426950408889634f * (v1[e] + b1[e]))); } }
;                     store8(rowp + bj * HALF, v0, v1);
.LBB0_798:
	v_mov_b32_e32 v60, v76
	v_mov_b32_e32 v61, v76
	v_pk_mul_f32 v[56:57], v[56:57], v[60:61]
	v_pk_mul_f32 v[54:55], v[54:55], v[76:77]
	v_pk_mul_f32 v[52:53], v[52:53], v[60:61]
	s_andn2_b64 vcc, exec, s[60:61]
	v_pk_mul_f32 v[50:51], v[50:51], v[76:77]
	s_cbranch_vccnz .LBB0_806
	s_and_b64 vcc, exec, s[10:11]
	s_cbranch_vccnz .LBB0_803
	s_andn2_b64 vcc, exec, s[84:85]
	v_mov_b32_e32 v61, v53
	v_mov_b32_e32 v60, v52
	v_mov_b32_e32 v63, v51
	v_mov_b32_e32 v62, v50
	v_mov_b32_e32 v65, v57
	v_mov_b32_e32 v64, v56
	v_mov_b32_e32 v75, v55
	v_mov_b32_e32 v74, v54
	s_cbranch_vccnz .LBB0_802
	s_movk_i32 s0, 0xb200
	v_lshl_add_u64 v[60:61], v[122:123], 2, v[146:147]
	s_mov_b32 s1, -1
	v_lshl_add_u64 v[64:65], v[60:61], 0, s[0:1]
	v_add_co_u32_e32 v60, vcc, 0xffffc000, v60
	s_nop 1
	v_addc_co_u32_e32 v61, vcc, -1, v61, vcc
	v_add_f32_e32 v60, v54, v218
	v_add_f32_e32 v64, v50, v222
	v_add_f32_e32 v61, v55, v219
	v_add_f32_e32 v65, v51, v223
	v_add_f32_e32 v62, v56, v220
	v_add_f32_e32 v74, v52, v224
	v_add_f32_e32 v63, v57, v221
	v_add_f32_e32 v75, v53, v225
	v_mul_f32_e32 v60, 0xbfb8aa3b, v60
	v_mul_f32_e32 v64, 0xbfb8aa3b, v64
	v_mul_f32_e32 v61, 0xbfb8aa3b, v61
	v_mul_f32_e32 v65, 0xbfb8aa3b, v65
	v_mul_f32_e32 v62, 0xbfb8aa3b, v62
	v_mul_f32_e32 v74, 0xbfb8aa3b, v74
	v_mul_f32_e32 v63, 0xbfb8aa3b, v63
	v_mul_f32_e32 v75, 0xbfb8aa3b, v75
	v_exp_f32_e32 v60, v60
	v_exp_f32_e32 v64, v64
	v_exp_f32_e32 v61, v61
	v_exp_f32_e32 v65, v65
	v_exp_f32_e32 v62, v62
	v_exp_f32_e32 v74, v74
	v_exp_f32_e32 v63, v63
	v_exp_f32_e32 v75, v75
	v_add_f32_e32 v60, 1.0, v60
	v_add_f32_e32 v64, 1.0, v64
	v_add_f32_e32 v61, 1.0, v61
	v_add_f32_e32 v65, 1.0, v65
	v_add_f32_e32 v76, 1.0, v62
	v_add_f32_e32 v77, 1.0, v74
	v_add_f32_e32 v78, 1.0, v63
	v_add_f32_e32 v79, 1.0, v75
	v_rcp_f32_e32 v74, v60
	v_rcp_f32_e32 v62, v64
	v_rcp_f32_e32 v75, v61
	v_rcp_f32_e32 v63, v65
	v_rcp_f32_e32 v64, v76
	v_rcp_f32_e32 v60, v77
	v_rcp_f32_e32 v65, v78
	v_rcp_f32_e32 v61, v79

;     __device__ __forceinline__ void operator()(const f32x4 (&acc)[2][2][4][2], const Unit& u, int wr, int wc, int fr, int fq) const {
;     ...
;                 const int row = row0 + ai * HALF + m * 16, pos = row & (SEQ - 1);
;                 bf16_t* rowp = P + (size_t)row * NIN + col0;
;                 const float rstd = rsqrtf(ssq_x[row] * (1.f / DM) + EPS);
.LBB0_812:
	s_cmp_lt_i32 s45, 4
	s_cbranch_scc1 .LBB0_817
	s_cmp_eq_u32 s45, 4
	s_cselect_b64 s[14:15], -1, 0
	s_cbranch_execz .LBB0_818
	v_mov_b64_e32 v[54:55], v[150:151]
	s_waitcnt lgkmcnt(0)
	v_mov_b64_e32 v[50:51], v[148:149]
	s_mov_b32 s0, s45
	v_add_u32_e32 v58, 0x90, v160
	s_and_b64 vcc, exec, s[14:15]
	s_cbranch_vccnz .LBB0_821
.LBB0_815:
	v_mov_b32_e32 v50, 1.0
	v_mov_b32_e32 v54, 0
	v_mov_b32_e32 v55, v54
	v_mov_b32_e32 v56, v54
	v_mov_b32_e32 v57, v54
	v_mov_b32_e32 v51, v50
	v_mov_b32_e32 v52, v50
	v_mov_b32_e32 v53, v50
	v_fmamk_f32 v0, v207, 0x3a800000, v235
	s_cmp_lt_i32 s45, 4
	v_cmp_gt_f32_e64 s[14:15], s58, v0
	s_cbranch_scc0 .LBB0_822

;     __device__ __forceinline__ void operator()(const f32x4 (&acc)[2][2][4][2], const Unit& u, int wr, int wc, int fr, int fq) const {
;     ...
;                 const int row = row0 + ai * HALF + m * 16, pos = row & (SEQ - 1);
;                 bf16_t* rowp = P + (size_t)row * NIN + col0;
;                 const float rstd = rsqrtf(ssq_x[row] * (1.f / DM) + EPS);
;                 float ss = 0.f;
;                 f32x4 c4 = (f32x4){1.f, 1.f, 1.f, 1.f}, s4 = (f32x4){0.f, 0.f, 0.f, 0.f};
;                 if (type == 0) { const int a = 4 * (wc & 1) + fq; c4 = *(const f32x4*)(cos64 + pos * 32 + 4 * a); s4 = *(const f32x4*)(sin64 + pos * 32 + 4 * a); }
.LBB0_821:
	v_and_b32_e32 v0, 0x1fdf, v58
	v_lshlrev_b32_e32 v0, s0, v0
	v_lshlrev_b64 v[56:57], 2, v[0:1]
	v_lshl_add_u64 v[50:51], v[50:51], 0, v[56:57]
	v_lshl_add_u64 v[54:55], v[54:55], 0, v[56:57]
	global_load_dwordx4 v[50:53], v[50:51], off
	s_nop 0
	global_load_dwordx4 v[54:57], v[54:55], off
	v_fmamk_f32 v0, v207, 0x3a800000, v235
	s_cmp_lt_i32 s45, 4
	v_cmp_gt_f32_e64 s[14:15], s58, v0
	s_cbranch_scc1 .LBB0_816

;     __device__ __forceinline__ void operator()(const f32x4 (&acc)[2][2][4][2], const Unit& u, int wr, int wc, int fr, int fq) const {
;     ...
;                 const float rstd = rsqrtf(ssq_x[row] * (1.f / DM) + EPS);
;                 float ss = 0.f;
;                 f32x4 c4 = (f32x4){1.f, 1.f, 1.f, 1.f}, s4 = (f32x4){0.f, 0.f, 0.f, 0.f};
;                 if (type == 0) { const int a = 4 * (wc & 1) + fq; c4 = *(const f32x4*)(cos64 + pos * 32 + 4 * a); s4 = *(const f32x4*)(sin64 + pos * 32 + 4 * a); }
;                 else if (type == 4) { c4 = *(const f32x4*)(cos32 + pos * 16 + 4 * fq); s4 = *(const f32x4*)(sin32 + pos * 16 + 4 * fq); }
; #pragma unroll
;                 for (int bj = 0; bj < 2; ++bj) {
;                     f32x4 v0 = acc[ai][bj][m][0] * rstd, v1 = acc[ai][bj][m][1] * rstd;
;                     if (type == 0 || type == 4) { const f32x4 lo = v0 * c4 - v1 * s4, hi_ = v1 * c4 + v0 * s4; v0 = lo * qs; v1 = hi_ * qs; }
;                     else if (type == 2 || type == 3) { ss += (v0[0] * v0[0] + v0[1] * v0[1]) + (v0[2] * v0[2] + v0[3] * v0[3]) + (v1[0] * v1[0] + v1[1] * v1[1]) + (v1[2] * v1[2] + v1[3] * v1[3]); }
;                     else if (type == 5) { const float* bp = bgate + (col0 + bj * HALF - PC_GATE); const f32x4 b0 = *(const f32x4*)bp, b1 = *(const f32x4*)(bp + 4);
; #pragma unroll
;                         for (int e = 0; e < 4; ++e) { v0[e] = __builtin_amdgcn_rcpf(1.f + __builtin_amdgcn_exp2f(-1.4426950408889634f * (v0[e] + b0[e]))); v1[e] = __builtin_amdgcn_rcpf(1.f + __builtin_amdgcn_exp2f(-1.4426950408889634f * (v1[e] + b1[e]))); } }
.LBB0_824:
	v_mul_f32_e32 v59, 0x4b800000, v0
	v_cndmask_b32_e64 v0, v0, v59, s[14:15]
	v_rsq_f32_e32 v0, v0
	s_andn2_b64 vcc, exec, s[62:63]
	v_mul_f32_e32 v59, 0x45800000, v0
	v_cndmask_b32_e64 v60, v0, v59, s[14:15]
	v_pk_mul_f32 v[48:49], v[48:49], v[60:61] op_sel_hi:[1,0]
	v_pk_mul_f32 v[46:47], v[46:47], v[60:61] op_sel_hi:[1,0]
	v_pk_mul_f32 v[44:45], v[44:45], v[60:61] op_sel_hi:[1,0]
	v_pk_mul_f32 v[42:43], v[42:43], v[60:61] op_sel_hi:[1,0]
	s_cbranch_vccnz .LBB0_832
	s_and_b64 vcc, exec, s[10:11]
	s_cbranch_vccnz .LBB0_829
	s_andn2_b64 vcc, exec, s[84:85]
	v_mov_b32_e32 v63, v45
	v_mov_b32_e32 v62, v44
	v_mov_b32_e32 v65, v43
	v_mov_b32_e32 v64, v42
	v_mov_b32_e32 v67, v49
	v_mov_b32_e32 v66, v48
	v_mov_b32_e32 v69, v47
	v_mov_b32_e32 v68, v46
	s_cbranch_vccnz .LBB0_828
	s_movk_i32 s0, 0xb000
	v_lshl_add_u64 v[62:63], v[122:123], 2, v[146:147]
	s_mov_b32 s1, -1
	v_lshl_add_u64 v[66:67], v[62:63], 0, s[0:1]
	v_add_co_u32_e32 v62, vcc, 0xffffb000, v62
	s_nop 1
	v_addc_co_u32_e32 v63, vcc, -1, v63, vcc
	v_add_f32_e32 v0, v46, v210
	v_add_f32_e32 v59, v42, v214
	v_add_f32_e32 v61, v47, v211
	v_add_f32_e32 v62, v43, v215
	v_add_f32_e32 v63, v48, v212
	v_add_f32_e32 v64, v44, v216
	v_add_f32_e32 v65, v49, v213
	v_add_f32_e32 v66, v45, v217
	v_mul_f32_e32 v0, 0xbfb8aa3b, v0
	v_mul_f32_e32 v59, 0xbfb8aa3b, v59
	v_mul_f32_e32 v61, 0xbfb8aa3b, v61
	v_mul_f32_e32 v62, 0xbfb8aa3b, v62
	v_mul_f32_e32 v63, 0xbfb8aa3b, v63
	v_mul_f32_e32 v64, 0xbfb8aa3b, v64
	v_mul_f32_e32 v65, 0xbfb8aa3b, v65
	v_mul_f32_e32 v66, 0xbfb8aa3b, v66
	v_exp_f32_e32 v0, v0
	v_exp_f32_e32 v59, v59
	v_exp_f32_e32 v61, v61
	v_exp_f32_e32 v62, v62
	v_exp_f32_e32 v63, v63
	v_exp_f32_e32 v64, v64
	v_exp_f32_e32 v65, v65
	v_exp_f32_e32 v66, v66
	v_add_f32_e32 v0, 1.0, v0
	v_add_f32_e32 v59, 1.0, v59
	v_add_f32_e32 v61, 1.0, v61
	v_add_f32_e32 v62, 1.0, v62
	v_add_f32_e32 v63, 1.0, v63
	v_add_f32_e32 v67, 1.0, v64
	v_add_f32_e32 v70, 1.0, v65
	v_add_f32_e32 v71, 1.0, v66
	v_rcp_f32_e32 v68, v0
	v_rcp_f32_e32 v64, v59
	v_rcp_f32_e32 v69, v61
	v_rcp_f32_e32 v65, v62
	v_rcp_f32_e32 v66, v63
	v_rcp_f32_e32 v62, v67
	v_rcp_f32_e32 v67, v70
	v_rcp_f32_e32 v63, v71

;     __device__ __forceinline__ void operator()(const f32x4 (&acc)[2][2][4][2], const Unit& u, int wr, int wc, int fr, int fq) const {
;     ...
;                     else if (type == 5) { const float* bp = bgate + (col0 + bj * HALF - PC_GATE); const f32x4 b0 = *(const f32x4*)bp, b1 = *(const f32x4*)(bp + 4);
; #pragma unroll
;                         for (int e = 0; e < 4; ++e) { v0[e] = __builtin_amdgcn_rcpf(1.f + __builtin_amdgcn_exp2f(-1.4426950408889634f * (v0[e] + b0[e]))); v1[e] = __builtin_amdgcn_rcpf(1.f + __builtin_amdgcn_exp2f(-1.4426950408889634f * (v1[e] + b1[e]))); } }
;                     store8(rowp + bj * HALF, v0, v1);
.LBB0_838:
	v_mov_b32_e32 v44, v60
	v_mov_b32_e32 v45, v60
	v_pk_mul_f32 v[40:41], v[40:41], v[44:45]
	v_pk_mul_f32 v[38:39], v[38:39], v[60:61]
	v_pk_mul_f32 v[36:37], v[36:37], v[44:45]
	s_andn2_b64 vcc, exec, s[60:61]
	v_pk_mul_f32 v[34:35], v[34:35], v[60:61]
	s_cbranch_vccnz .LBB0_846
	s_and_b64 vcc, exec, s[10:11]
	s_cbranch_vccnz .LBB0_843
	s_andn2_b64 vcc, exec, s[84:85]
	v_mov_b32_e32 v45, v37
	v_mov_b32_e32 v44, v36
	v_mov_b32_e32 v47, v35
	v_mov_b32_e32 v46, v34
	v_mov_b32_e32 v49, v41
	v_mov_b32_e32 v48, v40
	v_mov_b32_e32 v59, v39
	v_mov_b32_e32 v58, v38
	s_cbranch_vccnz .LBB0_842
	s_movk_i32 s0, 0xb200
	v_lshl_add_u64 v[44:45], v[122:123], 2, v[146:147]
	s_mov_b32 s1, -1
	v_lshl_add_u64 v[48:49], v[44:45], 0, s[0:1]
	v_add_co_u32_e32 v44, vcc, 0xffffc000, v44
	s_nop 1
	v_addc_co_u32_e32 v45, vcc, -1, v45, vcc
	v_add_f32_e32 v44, v38, v218
	v_add_f32_e32 v48, v34, v222
	v_add_f32_e32 v45, v39, v219
	v_add_f32_e32 v49, v35, v223
	v_add_f32_e32 v46, v40, v220
	v_add_f32_e32 v58, v36, v224
	v_add_f32_e32 v47, v41, v221
	v_add_f32_e32 v59, v37, v225
	v_mul_f32_e32 v44, 0xbfb8aa3b, v44
	v_mul_f32_e32 v48, 0xbfb8aa3b, v48
	v_mul_f32_e32 v45, 0xbfb8aa3b, v45
	v_mul_f32_e32 v49, 0xbfb8aa3b, v49
	v_mul_f32_e32 v46, 0xbfb8aa3b, v46
	v_mul_f32_e32 v58, 0xbfb8aa3b, v58
	v_mul_f32_e32 v47, 0xbfb8aa3b, v47
	v_mul_f32_e32 v59, 0xbfb8aa3b, v59
	v_exp_f32_e32 v44, v44
	v_exp_f32_e32 v48, v48
	v_exp_f32_e32 v45, v45
	v_exp_f32_e32 v49, v49
	v_exp_f32_e32 v46, v46
	v_exp_f32_e32 v58, v58
	v_exp_f32_e32 v47, v47
	v_exp_f32_e32 v59, v59
	v_add_f32_e32 v44, 1.0, v44
	v_add_f32_e32 v48, 1.0, v48
	v_add_f32_e32 v45, 1.0, v45
	v_add_f32_e32 v49, 1.0, v49
	v_add_f32_e32 v60, 1.0, v46
	v_add_f32_e32 v61, 1.0, v58
	v_add_f32_e32 v62, 1.0, v47
	v_add_f32_e32 v63, 1.0, v59
	v_rcp_f32_e32 v58, v44
	v_rcp_f32_e32 v46, v48
	v_rcp_f32_e32 v59, v45
	v_rcp_f32_e32 v47, v49
	v_rcp_f32_e32 v48, v60
	v_rcp_f32_e32 v44, v61
	v_rcp_f32_e32 v49, v62
	v_rcp_f32_e32 v45, v63

;     __device__ __forceinline__ void operator()(const f32x4 (&acc)[2][2][4][2], const Unit& u, int wr, int wc, int fr, int fq) const {
;     ...
;                 const int row = row0 + ai * HALF + m * 16, pos = row & (SEQ - 1);
;                 bf16_t* rowp = P + (size_t)row * NIN + col0;
;                 const float rstd = rsqrtf(ssq_x[row] * (1.f / DM) + EPS);
.LBB0_852:
	s_cmp_lt_i32 s45, 4
	s_cbranch_scc1 .LBB0_857
	s_cmp_eq_u32 s45, 4
	s_cselect_b64 s[14:15], -1, 0
	s_cbranch_execz .LBB0_858
	v_mov_b64_e32 v[38:39], v[150:151]
	s_waitcnt lgkmcnt(0)
	v_mov_b64_e32 v[34:35], v[148:149]
	s_mov_b32 s0, s45
	v_add_u32_e32 v42, 0xa0, v160
	s_and_b64 vcc, exec, s[14:15]
	s_cbranch_vccnz .LBB0_861
.LBB0_855:
	v_mov_b32_e32 v34, 1.0
	v_mov_b32_e32 v38, 0
	v_mov_b32_e32 v39, v38
	v_mov_b32_e32 v40, v38
	v_mov_b32_e32 v41, v38
	v_mov_b32_e32 v35, v34
	v_mov_b32_e32 v36, v34
	v_mov_b32_e32 v37, v34
	v_fmamk_f32 v0, v208, 0x3a800000, v235
	s_cmp_lt_i32 s45, 4
	v_cmp_gt_f32_e64 s[14:15], s58, v0
	s_cbranch_scc0 .LBB0_862

;     __device__ __forceinline__ void operator()(const f32x4 (&acc)[2][2][4][2], const Unit& u, int wr, int wc, int fr, int fq) const {
;     ...
;                 const int row = row0 + ai * HALF + m * 16, pos = row & (SEQ - 1);
;                 bf16_t* rowp = P + (size_t)row * NIN + col0;
;                 const float rstd = rsqrtf(ssq_x[row] * (1.f / DM) + EPS);
;                 float ss = 0.f;
;                 f32x4 c4 = (f32x4){1.f, 1.f, 1.f, 1.f}, s4 = (f32x4){0.f, 0.f, 0.f, 0.f};
;                 if (type == 0) { const int a = 4 * (wc & 1) + fq; c4 = *(const f32x4*)(cos64 + pos * 32 + 4 * a); s4 = *(const f32x4*)(sin64 + pos * 32 + 4 * a); }
.LBB0_861:
	v_and_b32_e32 v0, 0x1fef, v42
	v_lshlrev_b32_e32 v0, s0, v0
	v_lshlrev_b64 v[40:41], 2, v[0:1]
	v_lshl_add_u64 v[34:35], v[34:35], 0, v[40:41]
	v_lshl_add_u64 v[38:39], v[38:39], 0, v[40:41]
	global_load_dwordx4 v[34:37], v[34:35], off
	s_nop 0
	global_load_dwordx4 v[38:41], v[38:39], off
	v_fmamk_f32 v0, v208, 0x3a800000, v235
	s_cmp_lt_i32 s45, 4
	v_cmp_gt_f32_e64 s[14:15], s58, v0
	s_cbranch_scc1 .LBB0_856

;     __device__ __forceinline__ void operator()(const f32x4 (&acc)[2][2][4][2], const Unit& u, int wr, int wc, int fr, int fq) const {
;     ...
;                 const float rstd = rsqrtf(ssq_x[row] * (1.f / DM) + EPS);
;                 float ss = 0.f;
;                 f32x4 c4 = (f32x4){1.f, 1.f, 1.f, 1.f}, s4 = (f32x4){0.f, 0.f, 0.f, 0.f};
;                 if (type == 0) { const int a = 4 * (wc & 1) + fq; c4 = *(const f32x4*)(cos64 + pos * 32 + 4 * a); s4 = *(const f32x4*)(sin64 + pos * 32 + 4 * a); }
;                 else if (type == 4) { c4 = *(const f32x4*)(cos32 + pos * 16 + 4 * fq); s4 = *(const f32x4*)(sin32 + pos * 16 + 4 * fq); }
; #pragma unroll
;                 for (int bj = 0; bj < 2; ++bj) {
;                     f32x4 v0 = acc[ai][bj][m][0] * rstd, v1 = acc[ai][bj][m][1] * rstd;
;                     if (type == 0 || type == 4) { const f32x4 lo = v0 * c4 - v1 * s4, hi_ = v1 * c4 + v0 * s4; v0 = lo * qs; v1 = hi_ * qs; }
;                     else if (type == 2 || type == 3) { ss += (v0[0] * v0[0] + v0[1] * v0[1]) + (v0[2] * v0[2] + v0[3] * v0[3]) + (v1[0] * v1[0] + v1[1] * v1[1]) + (v1[2] * v1[2] + v1[3] * v1[3]); }
;                     else if (type == 5) { const float* bp = bgate + (col0 + bj * HALF - PC_GATE); const f32x4 b0 = *(const f32x4*)bp, b1 = *(const f32x4*)(bp + 4);
; #pragma unroll
;                         for (int e = 0; e < 4; ++e) { v0[e] = __builtin_amdgcn_rcpf(1.f + __builtin_amdgcn_exp2f(-1.4426950408889634f * (v0[e] + b0[e]))); v1[e] = __builtin_amdgcn_rcpf(1.f + __builtin_amdgcn_exp2f(-1.4426950408889634f * (v1[e] + b1[e]))); } }
.LBB0_864:
	v_mul_f32_e32 v43, 0x4b800000, v0
	v_cndmask_b32_e64 v0, v0, v43, s[14:15]
	v_rsq_f32_e32 v0, v0
	s_andn2_b64 vcc, exec, s[62:63]
	v_mul_f32_e32 v43, 0x45800000, v0
	v_cndmask_b32_e64 v44, v0, v43, s[14:15]
	v_pk_mul_f32 v[32:33], v[32:33], v[44:45] op_sel_hi:[1,0]
	v_pk_mul_f32 v[30:31], v[30:31], v[44:45] op_sel_hi:[1,0]
	v_pk_mul_f32 v[28:29], v[28:29], v[44:45] op_sel_hi:[1,0]
	v_pk_mul_f32 v[26:27], v[26:27], v[44:45] op_sel_hi:[1,0]
	s_cbranch_vccnz .LBB0_872
	s_and_b64 vcc, exec, s[10:11]
	s_cbranch_vccnz .LBB0_869
	s_andn2_b64 vcc, exec, s[84:85]
	v_mov_b32_e32 v47, v29
	v_mov_b32_e32 v46, v28
	v_mov_b32_e32 v49, v27
	v_mov_b32_e32 v48, v26
	v_mov_b32_e32 v51, v33
	v_mov_b32_e32 v50, v32
	v_mov_b32_e32 v53, v31
	v_mov_b32_e32 v52, v30
	s_cbranch_vccnz .LBB0_868
	s_movk_i32 s0, 0xb000
	v_lshl_add_u64 v[46:47], v[122:123], 2, v[146:147]
	s_mov_b32 s1, -1
	v_lshl_add_u64 v[50:51], v[46:47], 0, s[0:1]
	v_add_co_u32_e32 v46, vcc, 0xffffb000, v46
	s_nop 1
	v_addc_co_u32_e32 v47, vcc, -1, v47, vcc
	v_add_f32_e32 v0, v30, v210
	v_add_f32_e32 v43, v26, v214
	v_add_f32_e32 v45, v31, v211
	v_add_f32_e32 v46, v27, v215
	v_add_f32_e32 v47, v32, v212
	v_add_f32_e32 v48, v28, v216
	v_add_f32_e32 v49, v33, v213
	v_add_f32_e32 v50, v29, v217
	v_mul_f32_e32 v0, 0xbfb8aa3b, v0
	v_mul_f32_e32 v43, 0xbfb8aa3b, v43
	v_mul_f32_e32 v45, 0xbfb8aa3b, v45
	v_mul_f32_e32 v46, 0xbfb8aa3b, v46
	v_mul_f32_e32 v47, 0xbfb8aa3b, v47
	v_mul_f32_e32 v48, 0xbfb8aa3b, v48
	v_mul_f32_e32 v49, 0xbfb8aa3b, v49
	v_mul_f32_e32 v50, 0xbfb8aa3b, v50
	v_exp_f32_e32 v0, v0
	v_exp_f32_e32 v43, v43
	v_exp_f32_e32 v45, v45
	v_exp_f32_e32 v46, v46
	v_exp_f32_e32 v47, v47
	v_exp_f32_e32 v48, v48
	v_exp_f32_e32 v49, v49
	v_exp_f32_e32 v50, v50
	v_add_f32_e32 v0, 1.0, v0
	v_add_f32_e32 v43, 1.0, v43
	v_add_f32_e32 v45, 1.0, v45
	v_add_f32_e32 v46, 1.0, v46
	v_add_f32_e32 v47, 1.0, v47
	v_add_f32_e32 v51, 1.0, v48
	v_add_f32_e32 v54, 1.0, v49
	v_add_f32_e32 v55, 1.0, v50
	v_rcp_f32_e32 v52, v0
	v_rcp_f32_e32 v48, v43
	v_rcp_f32_e32 v53, v45
	v_rcp_f32_e32 v49, v46
	v_rcp_f32_e32 v50, v47
	v_rcp_f32_e32 v46, v51
	v_rcp_f32_e32 v51, v54
	v_rcp_f32_e32 v47, v55

;     __device__ __forceinline__ void operator()(const f32x4 (&acc)[2][2][4][2], const Unit& u, int wr, int wc, int fr, int fq) const {
;     ...
;                     else if (type == 5) { const float* bp = bgate + (col0 + bj * HALF - PC_GATE); const f32x4 b0 = *(const f32x4*)bp, b1 = *(const f32x4*)(bp + 4);
; #pragma unroll
;                         for (int e = 0; e < 4; ++e) { v0[e] = __builtin_amdgcn_rcpf(1.f + __builtin_amdgcn_exp2f(-1.4426950408889634f * (v0[e] + b0[e]))); v1[e] = __builtin_amdgcn_rcpf(1.f + __builtin_amdgcn_exp2f(-1.4426950408889634f * (v1[e] + b1[e]))); } }
;                     store8(rowp + bj * HALF, v0, v1);
.LBB0_878:
	v_mov_b32_e32 v28, v44
	v_mov_b32_e32 v29, v44
	v_pk_mul_f32 v[24:25], v[24:25], v[28:29]
	v_pk_mul_f32 v[22:23], v[22:23], v[44:45]
	v_pk_mul_f32 v[20:21], v[20:21], v[28:29]
	s_andn2_b64 vcc, exec, s[60:61]
	v_pk_mul_f32 v[18:19], v[18:19], v[44:45]
	s_cbranch_vccnz .LBB0_886
	s_and_b64 vcc, exec, s[10:11]
	s_cbranch_vccnz .LBB0_883
	s_andn2_b64 vcc, exec, s[84:85]
	v_mov_b32_e32 v29, v21
	v_mov_b32_e32 v28, v20
	v_mov_b32_e32 v31, v19
	v_mov_b32_e32 v30, v18
	v_mov_b32_e32 v33, v25
	v_mov_b32_e32 v32, v24
	v_mov_b32_e32 v43, v23
	v_mov_b32_e32 v42, v22
	s_cbranch_vccnz .LBB0_882
	s_movk_i32 s0, 0xb200
	v_lshl_add_u64 v[28:29], v[122:123], 2, v[146:147]
	s_mov_b32 s1, -1
	v_lshl_add_u64 v[32:33], v[28:29], 0, s[0:1]
	v_add_co_u32_e32 v28, vcc, 0xffffc000, v28
	s_nop 1
	v_addc_co_u32_e32 v29, vcc, -1, v29, vcc
	v_add_f32_e32 v28, v22, v218
	v_add_f32_e32 v32, v18, v222
	v_add_f32_e32 v29, v23, v219
	v_add_f32_e32 v33, v19, v223
	v_add_f32_e32 v30, v24, v220
	v_add_f32_e32 v42, v20, v224
	v_add_f32_e32 v31, v25, v221
	v_add_f32_e32 v43, v21, v225
	v_mul_f32_e32 v28, 0xbfb8aa3b, v28
	v_mul_f32_e32 v32, 0xbfb8aa3b, v32
	v_mul_f32_e32 v29, 0xbfb8aa3b, v29
	v_mul_f32_e32 v33, 0xbfb8aa3b, v33
	v_mul_f32_e32 v30, 0xbfb8aa3b, v30
	v_mul_f32_e32 v42, 0xbfb8aa3b, v42
	v_mul_f32_e32 v31, 0xbfb8aa3b, v31
	v_mul_f32_e32 v43, 0xbfb8aa3b, v43
	v_exp_f32_e32 v28, v28
	v_exp_f32_e32 v32, v32
	v_exp_f32_e32 v29, v29
	v_exp_f32_e32 v33, v33
	v_exp_f32_e32 v30, v30
	v_exp_f32_e32 v42, v42
	v_exp_f32_e32 v31, v31
	v_exp_f32_e32 v43, v43
	v_add_f32_e32 v28, 1.0, v28
	v_add_f32_e32 v32, 1.0, v32
	v_add_f32_e32 v29, 1.0, v29
	v_add_f32_e32 v33, 1.0, v33
	v_add_f32_e32 v44, 1.0, v30
	v_add_f32_e32 v45, 1.0, v42
	v_add_f32_e32 v46, 1.0, v31
	v_add_f32_e32 v47, 1.0, v43
	v_rcp_f32_e32 v42, v28
	v_rcp_f32_e32 v30, v32
	v_rcp_f32_e32 v43, v29
	v_rcp_f32_e32 v31, v33
	v_rcp_f32_e32 v32, v44
	v_rcp_f32_e32 v28, v45
	v_rcp_f32_e32 v33, v46
	v_rcp_f32_e32 v29, v47

;     __device__ __forceinline__ void operator()(const f32x4 (&acc)[2][2][4][2], const Unit& u, int wr, int wc, int fr, int fq) const {
;     ...
;                 const int row = row0 + ai * HALF + m * 16, pos = row & (SEQ - 1);
;                 bf16_t* rowp = P + (size_t)row * NIN + col0;
;                 const float rstd = rsqrtf(ssq_x[row] * (1.f / DM) + EPS);
.LBB0_892:
	s_cmp_lt_i32 s45, 4
	s_cbranch_scc1 .LBB0_897
	s_cmp_eq_u32 s45, 4
	s_cselect_b64 s[14:15], -1, 0
	s_cbranch_execz .LBB0_898
	v_mov_b64_e32 v[22:23], v[150:151]
	s_waitcnt lgkmcnt(0)
	v_mov_b64_e32 v[18:19], v[148:149]
	s_mov_b32 s0, s45
	v_add_u32_e32 v26, 0xb0, v160
	s_and_b64 vcc, exec, s[14:15]
	s_cbranch_vccnz .LBB0_901
.LBB0_895:
	v_mov_b32_e32 v18, 1.0
	v_mov_b32_e32 v22, 0
	v_mov_b32_e32 v23, v22
	v_mov_b32_e32 v24, v22
	v_mov_b32_e32 v25, v22
	v_mov_b32_e32 v19, v18
	v_mov_b32_e32 v20, v18
	v_mov_b32_e32 v21, v18
	v_fmamk_f32 v0, v209, 0x3a800000, v235
	s_cmp_lt_i32 s45, 4
	v_cmp_gt_f32_e64 s[14:15], s58, v0
	s_cbranch_scc0 .LBB0_902

;     __device__ __forceinline__ void operator()(const f32x4 (&acc)[2][2][4][2], const Unit& u, int wr, int wc, int fr, int fq) const {
;     ...
;                 const int row = row0 + ai * HALF + m * 16, pos = row & (SEQ - 1);
;                 bf16_t* rowp = P + (size_t)row * NIN + col0;
;                 const float rstd = rsqrtf(ssq_x[row] * (1.f / DM) + EPS);
;                 float ss = 0.f;
;                 f32x4 c4 = (f32x4){1.f, 1.f, 1.f, 1.f}, s4 = (f32x4){0.f, 0.f, 0.f, 0.f};
;                 if (type == 0) { const int a = 4 * (wc & 1) + fq; c4 = *(const f32x4*)(cos64 + pos * 32 + 4 * a); s4 = *(const f32x4*)(sin64 + pos * 32 + 4 * a); }
.LBB0_901:
	v_and_b32_e32 v0, 0x1fff, v26
	v_lshlrev_b32_e32 v0, s0, v0
	v_lshlrev_b64 v[24:25], 2, v[0:1]
	v_lshl_add_u64 v[18:19], v[18:19], 0, v[24:25]
	v_lshl_add_u64 v[22:23], v[22:23], 0, v[24:25]
	global_load_dwordx4 v[18:21], v[18:19], off
	s_nop 0
	global_load_dwordx4 v[22:25], v[22:23], off
	v_fmamk_f32 v0, v209, 0x3a800000, v235
	s_cmp_lt_i32 s45, 4
	v_cmp_gt_f32_e64 s[14:15], s58, v0
	s_cbranch_scc1 .LBB0_896

;     __device__ __forceinline__ void operator()(const f32x4 (&acc)[2][2][4][2], const Unit& u, int wr, int wc, int fr, int fq) const {
;     ...
;                 const float rstd = rsqrtf(ssq_x[row] * (1.f / DM) + EPS);
;                 float ss = 0.f;
;                 f32x4 c4 = (f32x4){1.f, 1.f, 1.f, 1.f}, s4 = (f32x4){0.f, 0.f, 0.f, 0.f};
;                 if (type == 0) { const int a = 4 * (wc & 1) + fq; c4 = *(const f32x4*)(cos64 + pos * 32 + 4 * a); s4 = *(const f32x4*)(sin64 + pos * 32 + 4 * a); }
;                 else if (type == 4) { c4 = *(const f32x4*)(cos32 + pos * 16 + 4 * fq); s4 = *(const f32x4*)(sin32 + pos * 16 + 4 * fq); }
; #pragma unroll
;                 for (int bj = 0; bj < 2; ++bj) {
;                     f32x4 v0 = acc[ai][bj][m][0] * rstd, v1 = acc[ai][bj][m][1] * rstd;
;                     if (type == 0 || type == 4) { const f32x4 lo = v0 * c4 - v1 * s4, hi_ = v1 * c4 + v0 * s4; v0 = lo * qs; v1 = hi_ * qs; }
;                     else if (type == 2 || type == 3) { ss += (v0[0] * v0[0] + v0[1] * v0[1]) + (v0[2] * v0[2] + v0[3] * v0[3]) + (v1[0] * v1[0] + v1[1] * v1[1]) + (v1[2] * v1[2] + v1[3] * v1[3]); }
;                     else if (type == 5) { const float* bp = bgate + (col0 + bj * HALF - PC_GATE); const f32x4 b0 = *(const f32x4*)bp, b1 = *(const f32x4*)(bp + 4);
; #pragma unroll
;                         for (int e = 0; e < 4; ++e) { v0[e] = __builtin_amdgcn_rcpf(1.f + __builtin_amdgcn_exp2f(-1.4426950408889634f * (v0[e] + b0[e]))); v1[e] = __builtin_amdgcn_rcpf(1.f + __builtin_amdgcn_exp2f(-1.4426950408889634f * (v1[e] + b1[e]))); } }
.LBB0_904:
	v_mul_f32_e32 v27, 0x4b800000, v0
	v_cndmask_b32_e64 v0, v0, v27, s[14:15]
	v_rsq_f32_e32 v0, v0
	s_andn2_b64 vcc, exec, s[62:63]
	v_mul_f32_e32 v27, 0x45800000, v0
	v_cndmask_b32_e64 v28, v0, v27, s[14:15]
	v_pk_mul_f32 v[16:17], v[16:17], v[28:29] op_sel_hi:[1,0]
	v_pk_mul_f32 v[14:15], v[14:15], v[28:29] op_sel_hi:[1,0]
	v_pk_mul_f32 v[12:13], v[12:13], v[28:29] op_sel_hi:[1,0]
	v_pk_mul_f32 v[10:11], v[10:11], v[28:29] op_sel_hi:[1,0]
	s_cbranch_vccnz .LBB0_912
	s_and_b64 vcc, exec, s[10:11]
	s_cbranch_vccnz .LBB0_909
	s_andn2_b64 vcc, exec, s[84:85]
	v_mov_b32_e32 v31, v13
	v_mov_b32_e32 v30, v12
	v_mov_b32_e32 v33, v11
	v_mov_b32_e32 v32, v10
	v_mov_b32_e32 v35, v17
	v_mov_b32_e32 v34, v16
	v_mov_b32_e32 v37, v15
	v_mov_b32_e32 v36, v14
	s_cbranch_vccnz .LBB0_908
	s_movk_i32 s0, 0xb000
	v_lshl_add_u64 v[30:31], v[122:123], 2, v[146:147]
	s_mov_b32 s1, -1
	v_lshl_add_u64 v[34:35], v[30:31], 0, s[0:1]
	v_add_co_u32_e32 v30, vcc, 0xffffb000, v30
	s_nop 1
	v_addc_co_u32_e32 v31, vcc, -1, v31, vcc
	v_add_f32_e32 v0, v14, v210
	v_add_f32_e32 v27, v10, v214
	v_add_f32_e32 v29, v15, v211
	v_add_f32_e32 v30, v11, v215
	v_add_f32_e32 v31, v16, v212
	v_add_f32_e32 v32, v12, v216
	v_add_f32_e32 v33, v17, v213
	v_add_f32_e32 v34, v13, v217
	v_mul_f32_e32 v0, 0xbfb8aa3b, v0
	v_mul_f32_e32 v27, 0xbfb8aa3b, v27
	v_mul_f32_e32 v29, 0xbfb8aa3b, v29
	v_mul_f32_e32 v30, 0xbfb8aa3b, v30
	v_mul_f32_e32 v31, 0xbfb8aa3b, v31
	v_mul_f32_e32 v32, 0xbfb8aa3b, v32
	v_mul_f32_e32 v33, 0xbfb8aa3b, v33
	v_mul_f32_e32 v34, 0xbfb8aa3b, v34
	v_exp_f32_e32 v0, v0
	v_exp_f32_e32 v27, v27
	v_exp_f32_e32 v29, v29
	v_exp_f32_e32 v30, v30
	v_exp_f32_e32 v31, v31
	v_exp_f32_e32 v32, v32
	v_exp_f32_e32 v33, v33
	v_exp_f32_e32 v34, v34
	v_add_f32_e32 v0, 1.0, v0
	v_add_f32_e32 v27, 1.0, v27
	v_add_f32_e32 v29, 1.0, v29
	v_add_f32_e32 v30, 1.0, v30
	v_add_f32_e32 v31, 1.0, v31
	v_add_f32_e32 v35, 1.0, v32
	v_add_f32_e32 v38, 1.0, v33
	v_add_f32_e32 v39, 1.0, v34
	v_rcp_f32_e32 v36, v0
	v_rcp_f32_e32 v32, v27
	v_rcp_f32_e32 v37, v29
	v_rcp_f32_e32 v33, v30
	v_rcp_f32_e32 v34, v31
	v_rcp_f32_e32 v30, v35
	v_rcp_f32_e32 v35, v38
	v_rcp_f32_e32 v31, v39

;     __device__ __forceinline__ void operator()(const f32x4 (&acc)[2][2][4][2], const Unit& u, int wr, int wc, int fr, int fq) const {
;     ...
;                     else if (type == 5) { const float* bp = bgate + (col0 + bj * HALF - PC_GATE); const f32x4 b0 = *(const f32x4*)bp, b1 = *(const f32x4*)(bp + 4);
; #pragma unroll
;                         for (int e = 0; e < 4; ++e) { v0[e] = __builtin_amdgcn_rcpf(1.f + __builtin_amdgcn_exp2f(-1.4426950408889634f * (v0[e] + b0[e]))); v1[e] = __builtin_amdgcn_rcpf(1.f + __builtin_amdgcn_exp2f(-1.4426950408889634f * (v1[e] + b1[e]))); } }
;                     store8(rowp + bj * HALF, v0, v1);
.LBB0_918:
	v_mov_b32_e32 v12, v28
	v_mov_b32_e32 v13, v28
	v_pk_mul_f32 v[8:9], v[8:9], v[12:13]
	v_pk_mul_f32 v[6:7], v[6:7], v[28:29]
	v_pk_mul_f32 v[4:5], v[4:5], v[12:13]
	s_andn2_b64 vcc, exec, s[60:61]
	v_pk_mul_f32 v[2:3], v[2:3], v[28:29]
	s_cbranch_vccnz .LBB0_926
	s_and_b64 vcc, exec, s[10:11]
	s_cbranch_vccnz .LBB0_923
	s_andn2_b64 vcc, exec, s[84:85]
	v_mov_b32_e32 v13, v5
	v_mov_b32_e32 v12, v4
	v_mov_b32_e32 v15, v3
	v_mov_b32_e32 v14, v2
	v_mov_b32_e32 v17, v9
	v_mov_b32_e32 v16, v8
	v_mov_b32_e32 v27, v7
	v_mov_b32_e32 v26, v6
	s_cbranch_vccnz .LBB0_922
	s_movk_i32 s0, 0xb200
	v_lshl_add_u64 v[12:13], v[122:123], 2, v[146:147]
	s_mov_b32 s1, -1
	v_lshl_add_u64 v[16:17], v[12:13], 0, s[0:1]
	v_add_co_u32_e32 v12, vcc, 0xffffc000, v12
	s_nop 1
	v_addc_co_u32_e32 v13, vcc, -1, v13, vcc
	v_add_f32_e32 v12, v6, v218
	v_add_f32_e32 v16, v2, v222
	v_add_f32_e32 v13, v7, v219
	v_add_f32_e32 v17, v3, v223
	v_add_f32_e32 v14, v8, v220
	v_add_f32_e32 v26, v4, v224
	v_add_f32_e32 v15, v9, v221
	v_add_f32_e32 v27, v5, v225
	v_mul_f32_e32 v12, 0xbfb8aa3b, v12
	v_mul_f32_e32 v16, 0xbfb8aa3b, v16
	v_mul_f32_e32 v13, 0xbfb8aa3b, v13
	v_mul_f32_e32 v17, 0xbfb8aa3b, v17
	v_mul_f32_e32 v14, 0xbfb8aa3b, v14
	v_mul_f32_e32 v26, 0xbfb8aa3b, v26
	v_mul_f32_e32 v15, 0xbfb8aa3b, v15
	v_mul_f32_e32 v27, 0xbfb8aa3b, v27
	v_exp_f32_e32 v12, v12
	v_exp_f32_e32 v16, v16
	v_exp_f32_e32 v13, v13
	v_exp_f32_e32 v17, v17
	v_exp_f32_e32 v14, v14
	v_exp_f32_e32 v26, v26
	v_exp_f32_e32 v15, v15
	v_exp_f32_e32 v27, v27
	v_add_f32_e32 v12, 1.0, v12
	v_add_f32_e32 v16, 1.0, v16
	v_add_f32_e32 v13, 1.0, v13
	v_add_f32_e32 v17, 1.0, v17
	v_add_f32_e32 v28, 1.0, v14
	v_add_f32_e32 v29, 1.0, v26
	v_add_f32_e32 v30, 1.0, v15
	v_add_f32_e32 v31, 1.0, v27
	v_rcp_f32_e32 v26, v12
	v_rcp_f32_e32 v14, v16
	v_rcp_f32_e32 v27, v13
	v_rcp_f32_e32 v15, v17
	v_rcp_f32_e32 v16, v28
	v_rcp_f32_e32 v12, v29
	v_rcp_f32_e32 v17, v30
	v_rcp_f32_e32 v13, v31
